# hand-off version with the load phase's vmcnt(8) and lgkmcnt(0) waits merged into a single s_waitcnt before the phase barrier
# speedup vs baseline: 1.0011x; 1.0011x over previous
; #define PG8_STAGE(bufoff, gbase, voff) do { _Pragma("unroll") for (int _i = 0; _i < 2; ++_i) \
;         __builtin_amdgcn_global_load_lds((const unsigned*)((const char*)(gbase) + (voff)[_i]), (LAS unsigned*)(lds + (bufoff) + ldsw + _i * 8192), 16, 0, 0); } while (0)
; #define PG8_LDA(dst, b, h) do { _Pragma("unroll") for (int m = 0; m < 4; ++m) _Pragma("unroll") for (int k = 0; k < 2; ++k) dst[m][k] = *(const LAS bf16x8*)(lds + PG8_SA(b, h) + aoff + m * 2048 + k * 1024); } while (0)
; #define PG8_LDB(dst, b, h) do { _Pragma("unroll") for (int n = 0; n < 2; ++n) _Pragma("unroll") for (int k = 0; k < 2; ++k) dst[n][k] = *(const LAS bf16x8*)(lds + PG8_SB(b, h) + boff + n * 2048 + k * 1024); } while (0)
; #define PG8_MMA(ai, bj, At, Bt) do { __builtin_amdgcn_s_setprio(1); _Pragma("unroll") for (int m = 0; m < 4; ++m) _Pragma("unroll") for (int n = 0; n < 2; ++n) _Pragma("unroll") for (int k = 0; k < 2; ++k) \
;         acc[ai][bj][m][n] = __builtin_amdgcn_mfma_f32_16x16x32_bf16(Bt[n][k], At[m][k], acc[ai][bj][m][n], 0, 0, 0); __builtin_amdgcn_s_setprio(0); } while (0)
; #define PG8_WAIT_V(n) asm volatile("s_waitcnt vmcnt(" #n ")" ::: "memory")
; #define PG8_WAIT_L(n) asm volatile("s_waitcnt lgkmcnt(" #n ")" ::: "memory")
; #define PG8_BAR __builtin_amdgcn_s_barrier()
; #define PG8_SCHED __builtin_amdgcn_sched_barrier(0)
; template <class Epi, class Sched>
; __device__ __forceinline__ void gemm_phase(LAS unsigned char* lds, const int K, const Sched& S, const Epi& E) {
;     ...
;         for (int t = 0; t < nt; t += 2) {
;             const bool last = (t == nt - 2);
;             const char* a1 = cA + (size_t)(t + 1) * kstep;
;             const char* a2 = last ? nA : cA + (size_t)(t + 2) * kstep; const char* b2 = last ? nB : cB + (size_t)(t + 2) * kstep;
;             const char* a3 = a2 + kstep; const char* b3 = b2 + kstep;
;             PG8_LDB(B0, 0, 0); PG8_LDB(B1, 0, 1); PG8_SCHED; PG8_LDA(At, 0, 0); PG8_STAGE(PG8_SA(1, 1), a1 + hstep, voffA);
;             PG8_WAIT_V(8); PG8_WAIT_L(0); PG8_BAR; PG8_MMA(0, 0, At, B0); PG8_MMA(0, 1, At, B1); PG8_BAR; PG8_SCHED;
;             PG8_LDA(At, 0, 1); PG8_STAGE(PG8_SB(0, 0), b2, voffB); PG8_STAGE(PG8_SB(0, 1), b2 + hstep, voffB); PG8_STAGE(PG8_SA(0, 0), a2, voffA);
;             PG8_WAIT_V(8); PG8_WAIT_L(0); PG8_BAR; PG8_MMA(1, 0, At, B0); PG8_MMA(1, 1, At, B1); PG8_BAR; PG8_SCHED;
.LBB0_403:
	s_add_u32 s14, s8, 0xfffc0080
	s_addc_u32 s15, s9, -1
	s_add_i32 s16, 0, 0x10000
	s_cmp_eq_u32 s13, 12
	s_cselect_b32 s55, s2, s15
	s_cselect_b32 s54, s4, s14
	v_add_u32_e32 v128, s16, v149
	s_cselect_b32 s39, s5, s12
	s_cselect_b32 s38, s10, s11
	s_add_i32 s17, 0, 0x14000
	ds_read_b128 v[158:161], v128
	ds_read_b128 v[162:165], v128 offset:1024
	ds_read_b128 v[184:187], v128 offset:2048
	ds_read_b128 v[188:191], v128 offset:3072
	v_add_u32_e32 v128, s17, v149
	ds_read_b128 v[192:195], v128
	ds_read_b128 v[196:199], v128 offset:1024
	ds_read_b128 v[200:203], v128 offset:2048
	ds_read_b128 v[204:207], v128 offset:3072
	v_lshl_add_u64 v[166:167], s[8:9], 0, v[154:155]
	s_add_i32 m0, s59, 0xc000
	ds_read_b128 v[208:211], v147
	ds_read_b128 v[212:215], v147 offset:1024
	ds_read_b128 v[216:219], v147 offset:2048
	ds_read_b128 v[220:223], v147 offset:3072
	ds_read_b128 v[224:227], v147 offset:4096
	ds_read_b128 v[228:231], v147 offset:5120
	ds_read_b128 v[232:235], v147 offset:6144
	ds_read_b128 v[236:239], v147 offset:7168
	global_load_lds_dwordx4 v[166:167], off
	v_lshl_add_u64 v[166:167], s[8:9], 0, v[156:157]
	s_add_i32 m0, s59, 0xe000
	s_nop 0
	global_load_lds_dwordx4 v[166:167], off
	s_waitcnt vmcnt(8) lgkmcnt(0)
	s_setprio 1
	s_barrier
	v_mfma_f32_16x16x32_bf16 v[124:127], v[158:161], v[208:211], v[124:127]
	v_mfma_f32_16x16x32_bf16 v[120:123], v[184:187], v[208:211], v[120:123]
	v_mfma_f32_16x16x32_bf16 v[108:111], v[158:161], v[216:219], v[108:111]
	v_mfma_f32_16x16x32_bf16 v[104:107], v[184:187], v[216:219], v[104:107]
	v_mfma_f32_16x16x32_bf16 v[92:95], v[158:161], v[224:227], v[92:95]
	v_mfma_f32_16x16x32_bf16 v[88:91], v[184:187], v[224:227], v[88:91]
	v_mfma_f32_16x16x32_bf16 v[76:79], v[158:161], v[232:235], v[76:79]
	v_mfma_f32_16x16x32_bf16 v[72:75], v[184:187], v[232:235], v[72:75]
	v_mfma_f32_16x16x32_bf16 v[124:127], v[162:165], v[212:215], v[124:127]
	v_mfma_f32_16x16x32_bf16 v[120:123], v[188:191], v[212:215], v[120:123]
	v_mfma_f32_16x16x32_bf16 v[108:111], v[162:165], v[220:223], v[108:111]
	v_mfma_f32_16x16x32_bf16 v[104:107], v[188:191], v[220:223], v[104:107]
	v_mfma_f32_16x16x32_bf16 v[92:95], v[162:165], v[228:231], v[92:95]
	v_mfma_f32_16x16x32_bf16 v[88:91], v[188:191], v[228:231], v[88:91]
	v_mfma_f32_16x16x32_bf16 v[76:79], v[162:165], v[236:239], v[76:79]
	v_mfma_f32_16x16x32_bf16 v[72:75], v[188:191], v[236:239], v[72:75]
	s_setprio 0
	s_setprio 1
	v_mfma_f32_16x16x32_bf16 v[116:119], v[192:195], v[208:211], v[116:119]
	v_mfma_f32_16x16x32_bf16 v[112:115], v[200:203], v[208:211], v[112:115]
	v_mfma_f32_16x16x32_bf16 v[100:103], v[192:195], v[216:219], v[100:103]
	v_mfma_f32_16x16x32_bf16 v[96:99], v[200:203], v[216:219], v[96:99]
	v_mfma_f32_16x16x32_bf16 v[84:87], v[192:195], v[224:227], v[84:87]
	v_mfma_f32_16x16x32_bf16 v[80:83], v[200:203], v[224:227], v[80:83]
	v_mfma_f32_16x16x32_bf16 v[68:71], v[192:195], v[232:235], v[68:71]
	v_mfma_f32_16x16x32_bf16 v[64:67], v[200:203], v[232:235], v[64:67]
	v_mfma_f32_16x16x32_bf16 v[116:119], v[196:199], v[212:215], v[116:119]
	v_mfma_f32_16x16x32_bf16 v[112:115], v[204:207], v[212:215], v[112:115]
	v_mfma_f32_16x16x32_bf16 v[100:103], v[196:199], v[220:223], v[100:103]
	v_mfma_f32_16x16x32_bf16 v[96:99], v[204:207], v[220:223], v[96:99]
	v_mfma_f32_16x16x32_bf16 v[84:87], v[196:199], v[228:231], v[84:87]
	v_mfma_f32_16x16x32_bf16 v[80:83], v[204:207], v[228:231], v[80:83]
	v_mfma_f32_16x16x32_bf16 v[68:71], v[196:199], v[236:239], v[68:71]
	v_mfma_f32_16x16x32_bf16 v[64:67], v[204:207], v[236:239], v[64:67]
	s_barrier
	s_setprio 0
	s_add_i32 s14, s16, s58
	v_lshl_add_u64 v[166:167], s[38:39], 0, v[140:141]
	s_mov_b32 m0, s14
	ds_read_b128 v[208:211], v147 offset:16384
	ds_read_b128 v[212:215], v147 offset:17408
	ds_read_b128 v[216:219], v147 offset:18432
	ds_read_b128 v[220:223], v147 offset:19456
	ds_read_b128 v[224:227], v147 offset:20480
	ds_read_b128 v[228:231], v147 offset:21504
	ds_read_b128 v[232:235], v147 offset:22528
	ds_read_b128 v[236:239], v147 offset:23552
	global_load_lds_dwordx4 v[166:167], off
	s_add_i32 m0, s14, 0x2000
	s_add_u32 s14, s38, 0x40000
	v_lshl_add_u64 v[180:181], s[38:39], 0, v[144:145]
	s_addc_u32 s15, s39, 0
	s_add_i32 s16, s17, s58
	global_load_lds_dwordx4 v[180:181], off
	v_lshl_add_u64 v[182:183], s[14:15], 0, v[140:141]
	s_mov_b32 m0, s16
	v_lshl_add_u64 v[240:241], s[54:55], 0, v[142:143]
	global_load_lds_dwordx4 v[182:183], off
	v_lshl_add_u64 v[182:183], s[14:15], 0, v[144:145]
	s_add_i32 m0, s16, 0x2000
	s_nop 0
	global_load_lds_dwordx4 v[182:183], off
	v_lshl_add_u64 v[182:183], s[54:55], 0, v[138:139]
	s_mov_b32 m0, s59
	s_nop 0
	global_load_lds_dwordx4 v[182:183], off
	s_mov_b32 m0, s60
	s_nop 0
	global_load_lds_dwordx4 v[240:241], off
	s_waitcnt vmcnt(8) lgkmcnt(0)
	s_setprio 1
	s_barrier
; #define PG8_STAGE(bufoff, gbase, voff) do { _Pragma("unroll") for (int _i = 0; _i < 2; ++_i) \
;         __builtin_amdgcn_global_load_lds((const unsigned*)((const char*)(gbase) + (voff)[_i]), (LAS unsigned*)(lds + (bufoff) + ldsw + _i * 8192), 16, 0, 0); } while (0)
; #define PG8_LDA(dst, b, h) do { _Pragma("unroll") for (int m = 0; m < 4; ++m) _Pragma("unroll") for (int k = 0; k < 2; ++k) dst[m][k] = *(const LAS bf16x8*)(lds + PG8_SA(b, h) + aoff + m * 2048 + k * 1024); } while (0)
; #define PG8_LDB(dst, b, h) do { _Pragma("unroll") for (int n = 0; n < 2; ++n) _Pragma("unroll") for (int k = 0; k < 2; ++k) dst[n][k] = *(const LAS bf16x8*)(lds + PG8_SB(b, h) + boff + n * 2048 + k * 1024); } while (0)
; #define PG8_MMA(ai, bj, At, Bt) do { __builtin_amdgcn_s_setprio(1); _Pragma("unroll") for (int m = 0; m < 4; ++m) _Pragma("unroll") for (int n = 0; n < 2; ++n) _Pragma("unroll") for (int k = 0; k < 2; ++k) \
;         acc[ai][bj][m][n] = __builtin_amdgcn_mfma_f32_16x16x32_bf16(Bt[n][k], At[m][k], acc[ai][bj][m][n], 0, 0, 0); __builtin_amdgcn_s_setprio(0); } while (0)
; #define PG8_WAIT_V(n) asm volatile("s_waitcnt vmcnt(" #n ")" ::: "memory")
; #define PG8_WAIT_L(n) asm volatile("s_waitcnt lgkmcnt(" #n ")" ::: "memory")
; #define PG8_BAR __builtin_amdgcn_s_barrier()
; #define PG8_SCHED __builtin_amdgcn_sched_barrier(0)
; template <class Epi, class Sched>
; __device__ __forceinline__ void gemm_phase(LAS unsigned char* lds, const int K, const Sched& S, const Epi& E) {
;     ...
;             PG8_WAIT_V(8); PG8_WAIT_L(0); PG8_BAR; PG8_MMA(1, 0, At, B0); PG8_MMA(1, 1, At, B1); PG8_BAR; PG8_SCHED;
;             PG8_LDB(B0, 1, 0); PG8_LDB(B1, 1, 1); PG8_SCHED; PG8_LDA(At, 1, 0); PG8_STAGE(PG8_SA(0, 1), a2 + hstep, voffA);
;             PG8_WAIT_V(8); PG8_WAIT_L(0); PG8_BAR; PG8_MMA(0, 0, At, B0); PG8_MMA(0, 1, At, B1); PG8_BAR; PG8_SCHED;
	v_mfma_f32_16x16x32_bf16 v[60:63], v[158:161], v[208:211], v[60:63]
	v_mfma_f32_16x16x32_bf16 v[56:59], v[184:187], v[208:211], v[56:59]
	v_mfma_f32_16x16x32_bf16 v[44:47], v[158:161], v[216:219], v[44:47]
	v_mfma_f32_16x16x32_bf16 v[40:43], v[184:187], v[216:219], v[40:43]
	v_mfma_f32_16x16x32_bf16 v[28:31], v[158:161], v[224:227], v[28:31]
	v_mfma_f32_16x16x32_bf16 v[24:27], v[184:187], v[224:227], v[24:27]
	v_mfma_f32_16x16x32_bf16 v[12:15], v[158:161], v[232:235], v[12:15]
	v_mfma_f32_16x16x32_bf16 v[8:11], v[184:187], v[232:235], v[8:11]
	v_mfma_f32_16x16x32_bf16 v[60:63], v[162:165], v[212:215], v[60:63]
	v_mfma_f32_16x16x32_bf16 v[56:59], v[188:191], v[212:215], v[56:59]
	v_mfma_f32_16x16x32_bf16 v[44:47], v[162:165], v[220:223], v[44:47]
	v_mfma_f32_16x16x32_bf16 v[40:43], v[188:191], v[220:223], v[40:43]
	v_mfma_f32_16x16x32_bf16 v[28:31], v[162:165], v[228:231], v[28:31]
	v_mfma_f32_16x16x32_bf16 v[24:27], v[188:191], v[228:231], v[24:27]
	v_mfma_f32_16x16x32_bf16 v[12:15], v[162:165], v[236:239], v[12:15]
	v_mfma_f32_16x16x32_bf16 v[8:11], v[188:191], v[236:239], v[8:11]
	s_setprio 0
	s_setprio 1
	v_mfma_f32_16x16x32_bf16 v[52:55], v[192:195], v[208:211], v[52:55]
	v_mfma_f32_16x16x32_bf16 v[48:51], v[200:203], v[208:211], v[48:51]
	v_mfma_f32_16x16x32_bf16 v[36:39], v[192:195], v[216:219], v[36:39]
	v_mfma_f32_16x16x32_bf16 v[32:35], v[200:203], v[216:219], v[32:35]
	v_mfma_f32_16x16x32_bf16 v[20:23], v[192:195], v[224:227], v[20:23]
	v_mfma_f32_16x16x32_bf16 v[16:19], v[200:203], v[224:227], v[16:19]
	v_mfma_f32_16x16x32_bf16 v[4:7], v[192:195], v[232:235], v[4:7]
	v_mfma_f32_16x16x32_bf16 v[0:3], v[200:203], v[232:235], v[0:3]
	v_mfma_f32_16x16x32_bf16 v[52:55], v[196:199], v[212:215], v[52:55]
	v_mfma_f32_16x16x32_bf16 v[48:51], v[204:207], v[212:215], v[48:51]
	v_mfma_f32_16x16x32_bf16 v[36:39], v[196:199], v[220:223], v[36:39]
	v_mfma_f32_16x16x32_bf16 v[32:35], v[204:207], v[220:223], v[32:35]
	v_mfma_f32_16x16x32_bf16 v[20:23], v[196:199], v[228:231], v[20:23]
	v_mfma_f32_16x16x32_bf16 v[16:19], v[204:207], v[228:231], v[16:19]
	v_mfma_f32_16x16x32_bf16 v[4:7], v[196:199], v[236:239], v[4:7]
	v_mfma_f32_16x16x32_bf16 v[0:3], v[204:207], v[236:239], v[0:3]
	s_barrier
	s_setprio 0
	s_add_i32 s16, 0, 0x18000
	v_add_u32_e32 v128, s16, v149
	s_add_i32 s17, 0, 0x1c000
	ds_read_b128 v[158:161], v128
	ds_read_b128 v[162:165], v128 offset:1024
	ds_read_b128 v[184:187], v128 offset:2048
	ds_read_b128 v[188:191], v128 offset:3072
	v_add_u32_e32 v128, s17, v149
	ds_read_b128 v[192:195], v128
	ds_read_b128 v[196:199], v128 offset:1024
	ds_read_b128 v[200:203], v128 offset:2048
	ds_read_b128 v[204:207], v128 offset:3072
	s_add_u32 s14, s54, 0x40000
	s_addc_u32 s15, s55, 0
	s_mov_b32 m0, s61
	v_lshl_add_u64 v[242:243], s[14:15], 0, v[138:139]
	ds_read_b128 v[208:211], v147 offset:32768
	ds_read_b128 v[212:215], v147 offset:33792
	ds_read_b128 v[216:219], v147 offset:34816
	ds_read_b128 v[220:223], v147 offset:35840
	ds_read_b128 v[224:227], v147 offset:36864
	ds_read_b128 v[228:231], v147 offset:37888
	ds_read_b128 v[232:235], v147 offset:38912
	ds_read_b128 v[236:239], v147 offset:39936
	global_load_lds_dwordx4 v[242:243], off
	v_lshl_add_u64 v[242:243], s[14:15], 0, v[142:143]
	s_mov_b32 m0, s62
	s_nop 0
	global_load_lds_dwordx4 v[242:243], off
	s_waitcnt vmcnt(8) lgkmcnt(0)
	s_setprio 1
	s_barrier
	v_mfma_f32_16x16x32_bf16 v[124:127], v[158:161], v[208:211], v[124:127]
	v_mfma_f32_16x16x32_bf16 v[120:123], v[184:187], v[208:211], v[120:123]
	v_mfma_f32_16x16x32_bf16 v[108:111], v[158:161], v[216:219], v[108:111]
	v_mfma_f32_16x16x32_bf16 v[104:107], v[184:187], v[216:219], v[104:107]
	v_mfma_f32_16x16x32_bf16 v[92:95], v[158:161], v[224:227], v[92:95]
	v_mfma_f32_16x16x32_bf16 v[88:91], v[184:187], v[224:227], v[88:91]
	v_mfma_f32_16x16x32_bf16 v[76:79], v[158:161], v[232:235], v[76:79]
	v_mfma_f32_16x16x32_bf16 v[72:75], v[184:187], v[232:235], v[72:75]
	v_mfma_f32_16x16x32_bf16 v[124:127], v[162:165], v[212:215], v[124:127]
	v_mfma_f32_16x16x32_bf16 v[120:123], v[188:191], v[212:215], v[120:123]
	v_mfma_f32_16x16x32_bf16 v[108:111], v[162:165], v[220:223], v[108:111]
	v_mfma_f32_16x16x32_bf16 v[104:107], v[188:191], v[220:223], v[104:107]
	v_mfma_f32_16x16x32_bf16 v[92:95], v[162:165], v[228:231], v[92:95]
	v_mfma_f32_16x16x32_bf16 v[88:91], v[188:191], v[228:231], v[88:91]
	v_mfma_f32_16x16x32_bf16 v[76:79], v[162:165], v[236:239], v[76:79]
	v_mfma_f32_16x16x32_bf16 v[72:75], v[188:191], v[236:239], v[72:75]
	s_setprio 0
	s_setprio 1
	v_mfma_f32_16x16x32_bf16 v[116:119], v[192:195], v[208:211], v[116:119]
	v_mfma_f32_16x16x32_bf16 v[112:115], v[200:203], v[208:211], v[112:115]
	v_mfma_f32_16x16x32_bf16 v[100:103], v[192:195], v[216:219], v[100:103]
	v_mfma_f32_16x16x32_bf16 v[96:99], v[200:203], v[216:219], v[96:99]
	v_mfma_f32_16x16x32_bf16 v[84:87], v[192:195], v[224:227], v[84:87]
	v_mfma_f32_16x16x32_bf16 v[80:83], v[200:203], v[224:227], v[80:83]
	v_mfma_f32_16x16x32_bf16 v[68:71], v[192:195], v[232:235], v[68:71]
	v_mfma_f32_16x16x32_bf16 v[64:67], v[200:203], v[232:235], v[64:67]
	v_mfma_f32_16x16x32_bf16 v[116:119], v[196:199], v[212:215], v[116:119]
	v_mfma_f32_16x16x32_bf16 v[112:115], v[204:207], v[212:215], v[112:115]
	v_mfma_f32_16x16x32_bf16 v[100:103], v[196:199], v[220:223], v[100:103]
	v_mfma_f32_16x16x32_bf16 v[96:99], v[204:207], v[220:223], v[96:99]
	v_mfma_f32_16x16x32_bf16 v[84:87], v[196:199], v[228:231], v[84:87]
	v_mfma_f32_16x16x32_bf16 v[80:83], v[204:207], v[228:231], v[80:83]
	v_mfma_f32_16x16x32_bf16 v[68:71], v[196:199], v[236:239], v[68:71]
	v_mfma_f32_16x16x32_bf16 v[64:67], v[204:207], v[236:239], v[64:67]
	s_barrier
; #define PG8_STAGE(bufoff, gbase, voff) do { _Pragma("unroll") for (int _i = 0; _i < 2; ++_i) \
;         __builtin_amdgcn_global_load_lds((const unsigned*)((const char*)(gbase) + (voff)[_i]), (LAS unsigned*)(lds + (bufoff) + ldsw + _i * 8192), 16, 0, 0); } while (0)
; #define PG8_LDA(dst, b, h) do { _Pragma("unroll") for (int m = 0; m < 4; ++m) _Pragma("unroll") for (int k = 0; k < 2; ++k) dst[m][k] = *(const LAS bf16x8*)(lds + PG8_SA(b, h) + aoff + m * 2048 + k * 1024); } while (0)
; #define PG8_MMA(ai, bj, At, Bt) do { __builtin_amdgcn_s_setprio(1); _Pragma("unroll") for (int m = 0; m < 4; ++m) _Pragma("unroll") for (int n = 0; n < 2; ++n) _Pragma("unroll") for (int k = 0; k < 2; ++k) \
;         acc[ai][bj][m][n] = __builtin_amdgcn_mfma_f32_16x16x32_bf16(Bt[n][k], At[m][k], acc[ai][bj][m][n], 0, 0, 0); __builtin_amdgcn_s_setprio(0); } while (0)
; #define PG8_WAIT_V(n) asm volatile("s_waitcnt vmcnt(" #n ")" ::: "memory")
; #define PG8_WAIT_L(n) asm volatile("s_waitcnt lgkmcnt(" #n ")" ::: "memory")
; #define PG8_BAR __builtin_amdgcn_s_barrier()
; #define PG8_SCHED __builtin_amdgcn_sched_barrier(0)
; template <class Epi, class Sched>
; __device__ __forceinline__ void gemm_phase(LAS unsigned char* lds, const int K, const Sched& S, const Epi& E) {
;     ...
;             PG8_LDA(At, 1, 1); PG8_STAGE(PG8_SB(1, 0), b3, voffB); PG8_STAGE(PG8_SB(1, 1), b3 + hstep, voffB); PG8_STAGE(PG8_SA(1, 0), a3, voffA);
;             PG8_WAIT_V(8); PG8_WAIT_L(0); PG8_BAR; PG8_MMA(1, 0, At, B0); PG8_MMA(1, 1, At, B1); PG8_BAR; PG8_SCHED;
;         }
;         if (wr == 0) PG8_BAR;
	s_setprio 0
	s_add_i32 s14, s16, s58
	v_lshl_add_u64 v[166:167], v[166:167], 0, s[36:37]
	s_mov_b32 m0, s14
	ds_read_b128 v[208:211], v147 offset:49152
	ds_read_b128 v[212:215], v147 offset:50176
	ds_read_b128 v[216:219], v147 offset:51200
	ds_read_b128 v[220:223], v147 offset:52224
	ds_read_b128 v[224:227], v147 offset:53248
	ds_read_b128 v[228:231], v147 offset:54272
	ds_read_b128 v[232:235], v147 offset:55296
	ds_read_b128 v[236:239], v147 offset:56320
	global_load_lds_dwordx4 v[166:167], off
	s_add_i32 m0, s14, 0x2000
	s_add_u32 s14, s38, 0x40080
	v_lshl_add_u64 v[166:167], v[180:181], 0, s[36:37]
	s_addc_u32 s15, s39, 0
	s_add_i32 s16, s17, s58
	global_load_lds_dwordx4 v[166:167], off
	v_lshl_add_u64 v[166:167], s[14:15], 0, v[140:141]
	s_mov_b32 m0, s16
	s_nop 0
	global_load_lds_dwordx4 v[166:167], off
	v_lshl_add_u64 v[166:167], s[14:15], 0, v[144:145]
	s_add_i32 m0, s16, 0x2000
	s_nop 0
	global_load_lds_dwordx4 v[166:167], off
	v_lshl_add_u64 v[166:167], v[182:183], 0, s[36:37]
	s_mov_b32 m0, s64
	s_nop 0
	global_load_lds_dwordx4 v[166:167], off
	v_lshl_add_u64 v[166:167], v[240:241], 0, s[36:37]
	s_mov_b32 m0, s65
	s_nop 0
	global_load_lds_dwordx4 v[166:167], off
	s_waitcnt vmcnt(8) lgkmcnt(0)
	s_setprio 1
	s_barrier
	v_mfma_f32_16x16x32_bf16 v[60:63], v[158:161], v[208:211], v[60:63]
	v_mfma_f32_16x16x32_bf16 v[56:59], v[184:187], v[208:211], v[56:59]
	v_mfma_f32_16x16x32_bf16 v[44:47], v[158:161], v[216:219], v[44:47]
	v_mfma_f32_16x16x32_bf16 v[40:43], v[184:187], v[216:219], v[40:43]
	v_mfma_f32_16x16x32_bf16 v[28:31], v[158:161], v[224:227], v[28:31]
	v_mfma_f32_16x16x32_bf16 v[24:27], v[184:187], v[224:227], v[24:27]
	v_mfma_f32_16x16x32_bf16 v[12:15], v[158:161], v[232:235], v[12:15]
	v_mfma_f32_16x16x32_bf16 v[8:11], v[184:187], v[232:235], v[8:11]
	v_mfma_f32_16x16x32_bf16 v[60:63], v[162:165], v[212:215], v[60:63]
	v_mfma_f32_16x16x32_bf16 v[56:59], v[188:191], v[212:215], v[56:59]
	v_mfma_f32_16x16x32_bf16 v[44:47], v[162:165], v[220:223], v[44:47]
	v_mfma_f32_16x16x32_bf16 v[40:43], v[188:191], v[220:223], v[40:43]
	v_mfma_f32_16x16x32_bf16 v[28:31], v[162:165], v[228:231], v[28:31]
	v_mfma_f32_16x16x32_bf16 v[24:27], v[188:191], v[228:231], v[24:27]
	v_mfma_f32_16x16x32_bf16 v[12:15], v[162:165], v[236:239], v[12:15]
	v_mfma_f32_16x16x32_bf16 v[8:11], v[188:191], v[236:239], v[8:11]
	s_setprio 0
	s_setprio 1
	v_mfma_f32_16x16x32_bf16 v[52:55], v[192:195], v[208:211], v[52:55]
	v_mfma_f32_16x16x32_bf16 v[48:51], v[200:203], v[208:211], v[48:51]
	v_mfma_f32_16x16x32_bf16 v[36:39], v[192:195], v[216:219], v[36:39]
	v_mfma_f32_16x16x32_bf16 v[32:35], v[200:203], v[216:219], v[32:35]
	v_mfma_f32_16x16x32_bf16 v[20:23], v[192:195], v[224:227], v[20:23]
	v_mfma_f32_16x16x32_bf16 v[16:19], v[200:203], v[224:227], v[16:19]
	v_mfma_f32_16x16x32_bf16 v[4:7], v[192:195], v[232:235], v[4:7]
	v_mfma_f32_16x16x32_bf16 v[0:3], v[200:203], v[232:235], v[0:3]
	v_mfma_f32_16x16x32_bf16 v[52:55], v[196:199], v[212:215], v[52:55]
	v_mfma_f32_16x16x32_bf16 v[48:51], v[204:207], v[212:215], v[48:51]
	v_mfma_f32_16x16x32_bf16 v[36:39], v[196:199], v[220:223], v[36:39]
	v_mfma_f32_16x16x32_bf16 v[32:35], v[204:207], v[220:223], v[32:35]
	v_mfma_f32_16x16x32_bf16 v[20:23], v[196:199], v[228:231], v[20:23]
	v_mfma_f32_16x16x32_bf16 v[16:19], v[204:207], v[228:231], v[16:19]
	v_mfma_f32_16x16x32_bf16 v[4:7], v[196:199], v[236:239], v[4:7]
	v_mfma_f32_16x16x32_bf16 v[0:3], v[204:207], v[236:239], v[0:3]
	s_barrier
	s_setprio 0
	s_add_i32 s13, s13, 2
	s_add_u32 s8, s8, 0x100
	s_addc_u32 s9, s9, 0
	s_add_u32 s11, s11, 0x100
	s_addc_u32 s12, s12, 0
	s_cmp_gt_u32 s13, 13
	s_cbranch_scc0 .LBB0_403
	s_and_b64 vcc, exec, s[42:43]
	s_cbranch_vccz .LBB0_406
	s_barrier

; #define PG8_STAGE(bufoff, gbase, voff) do { _Pragma("unroll") for (int _i = 0; _i < 2; ++_i) \
;         __builtin_amdgcn_global_load_lds((const unsigned*)((const char*)(gbase) + (voff)[_i]), (LAS unsigned*)(lds + (bufoff) + ldsw + _i * 8192), 16, 0, 0); } while (0)
; #define PG8_LDA(dst, b, h) do { _Pragma("unroll") for (int m = 0; m < 4; ++m) _Pragma("unroll") for (int k = 0; k < 2; ++k) dst[m][k] = *(const LAS bf16x8*)(lds + PG8_SA(b, h) + aoff + m * 2048 + k * 1024); } while (0)
; #define PG8_LDB(dst, b, h) do { _Pragma("unroll") for (int n = 0; n < 2; ++n) _Pragma("unroll") for (int k = 0; k < 2; ++k) dst[n][k] = *(const LAS bf16x8*)(lds + PG8_SB(b, h) + boff + n * 2048 + k * 1024); } while (0)
; #define PG8_MMA(ai, bj, At, Bt) do { __builtin_amdgcn_s_setprio(1); _Pragma("unroll") for (int m = 0; m < 4; ++m) _Pragma("unroll") for (int n = 0; n < 2; ++n) _Pragma("unroll") for (int k = 0; k < 2; ++k) \
;         acc[ai][bj][m][n] = __builtin_amdgcn_mfma_f32_16x16x32_bf16(Bt[n][k], At[m][k], acc[ai][bj][m][n], 0, 0, 0); __builtin_amdgcn_s_setprio(0); } while (0)
; #define PG8_WAIT_V(n) asm volatile("s_waitcnt vmcnt(" #n ")" ::: "memory")
; #define PG8_WAIT_L(n) asm volatile("s_waitcnt lgkmcnt(" #n ")" ::: "memory")
; #define PG8_BAR __builtin_amdgcn_s_barrier()
; #define PG8_SCHED __builtin_amdgcn_sched_barrier(0)
; template <class Epi, class Sched>
; __device__ __forceinline__ void gemm_phase(LAS unsigned char* lds, const int K, const Sched& S, const Epi& E) {
;     ...
;         for (int t = 0; t < nt; t += 2) {
;             const bool last = (t == nt - 2);
;             const char* a1 = cA + (size_t)(t + 1) * kstep;
;             const char* a2 = last ? nA : cA + (size_t)(t + 2) * kstep; const char* b2 = last ? nB : cB + (size_t)(t + 2) * kstep;
;             const char* a3 = a2 + kstep; const char* b3 = b2 + kstep;
;             PG8_LDB(B0, 0, 0); PG8_LDB(B1, 0, 1); PG8_SCHED; PG8_LDA(At, 0, 0); PG8_STAGE(PG8_SA(1, 1), a1 + hstep, voffA);
;             PG8_WAIT_V(8); PG8_WAIT_L(0); PG8_BAR; PG8_MMA(0, 0, At, B0); PG8_MMA(0, 1, At, B1); PG8_BAR; PG8_SCHED;
;             PG8_LDA(At, 0, 1); PG8_STAGE(PG8_SB(0, 0), b2, voffB); PG8_STAGE(PG8_SB(0, 1), b2 + hstep, voffB); PG8_STAGE(PG8_SA(0, 0), a2, voffA);
;             PG8_WAIT_V(8); PG8_WAIT_L(0); PG8_BAR; PG8_MMA(1, 0, At, B0); PG8_MMA(1, 1, At, B1); PG8_BAR; PG8_SCHED;
.LBB0_511:
	s_add_i32 s14, s8, 0xfaf9e080
	s_cmp_lg_u32 s13, 60
	s_cselect_b32 s14, s14, 0
	s_add_u32 s40, s28, s14
	s_addc_u32 s41, s29, 0
	s_add_i32 s15, 0, 0x10000
	s_add_u32 s38, s34, s14
	s_addc_u32 s39, s35, 0
	s_add_i32 s16, 0, 0x14000
	v_add_u32_e32 v164, s15, v145
	v_add_u32_e32 v180, s16, v145
	ds_read_b128 v[152:155], v164
	ds_read_b128 v[156:159], v164 offset:1024
	ds_read_b128 v[160:163], v164 offset:2048
	ds_read_b128 v[164:167], v164 offset:3072
	ds_read_b128 v[184:187], v180
	ds_read_b128 v[188:191], v180 offset:1024
	ds_read_b128 v[192:195], v180 offset:2048
	ds_read_b128 v[196:199], v180 offset:3072
	v_lshl_add_u64 v[180:181], v[146:147], 0, s[8:9]
	s_add_i32 m0, s2, 0xc000
	ds_read_b128 v[200:203], v151
	ds_read_b128 v[204:207], v151 offset:1024
	ds_read_b128 v[208:211], v151 offset:2048
	ds_read_b128 v[212:215], v151 offset:3072
	ds_read_b128 v[216:219], v151 offset:4096
	ds_read_b128 v[220:223], v151 offset:5120
	ds_read_b128 v[224:227], v151 offset:6144
	ds_read_b128 v[228:231], v151 offset:7168
	global_load_lds_dwordx4 v[180:181], off
	v_lshl_add_u64 v[180:181], v[148:149], 0, s[8:9]
	s_add_i32 m0, s2, 0xe000
	s_nop 0
	global_load_lds_dwordx4 v[180:181], off
	s_waitcnt vmcnt(8) lgkmcnt(0)
	s_setprio 1
	s_barrier
	v_mfma_f32_16x16x32_bf16 v[124:127], v[152:155], v[200:203], v[124:127]
	v_mfma_f32_16x16x32_bf16 v[120:123], v[160:163], v[200:203], v[120:123]
	v_mfma_f32_16x16x32_bf16 v[108:111], v[152:155], v[208:211], v[108:111]
	v_mfma_f32_16x16x32_bf16 v[104:107], v[160:163], v[208:211], v[104:107]
	v_mfma_f32_16x16x32_bf16 v[92:95], v[152:155], v[216:219], v[92:95]
	v_mfma_f32_16x16x32_bf16 v[88:91], v[160:163], v[216:219], v[88:91]
	v_mfma_f32_16x16x32_bf16 v[76:79], v[152:155], v[224:227], v[76:79]
	v_mfma_f32_16x16x32_bf16 v[72:75], v[160:163], v[224:227], v[72:75]
	v_mfma_f32_16x16x32_bf16 v[124:127], v[156:159], v[204:207], v[124:127]
	v_mfma_f32_16x16x32_bf16 v[120:123], v[164:167], v[204:207], v[120:123]
	v_mfma_f32_16x16x32_bf16 v[108:111], v[156:159], v[212:215], v[108:111]
	v_mfma_f32_16x16x32_bf16 v[104:107], v[164:167], v[212:215], v[104:107]
	v_mfma_f32_16x16x32_bf16 v[92:95], v[156:159], v[220:223], v[92:95]
	v_mfma_f32_16x16x32_bf16 v[88:91], v[164:167], v[220:223], v[88:91]
	v_mfma_f32_16x16x32_bf16 v[76:79], v[156:159], v[228:231], v[76:79]
	v_mfma_f32_16x16x32_bf16 v[72:75], v[164:167], v[228:231], v[72:75]
	s_setprio 0
	s_setprio 1
	v_mfma_f32_16x16x32_bf16 v[116:119], v[184:187], v[200:203], v[116:119]
	v_mfma_f32_16x16x32_bf16 v[112:115], v[192:195], v[200:203], v[112:115]
	v_mfma_f32_16x16x32_bf16 v[100:103], v[184:187], v[208:211], v[100:103]
	v_mfma_f32_16x16x32_bf16 v[96:99], v[192:195], v[208:211], v[96:99]
	v_mfma_f32_16x16x32_bf16 v[84:87], v[184:187], v[216:219], v[84:87]
	v_mfma_f32_16x16x32_bf16 v[80:83], v[192:195], v[216:219], v[80:83]
	v_mfma_f32_16x16x32_bf16 v[68:71], v[184:187], v[224:227], v[68:71]
	v_mfma_f32_16x16x32_bf16 v[64:67], v[192:195], v[224:227], v[64:67]
	v_mfma_f32_16x16x32_bf16 v[116:119], v[188:191], v[204:207], v[116:119]
	v_mfma_f32_16x16x32_bf16 v[112:115], v[196:199], v[204:207], v[112:115]
	v_mfma_f32_16x16x32_bf16 v[100:103], v[188:191], v[212:215], v[100:103]
	v_mfma_f32_16x16x32_bf16 v[96:99], v[196:199], v[212:215], v[96:99]
	v_mfma_f32_16x16x32_bf16 v[84:87], v[188:191], v[220:223], v[84:87]
	v_mfma_f32_16x16x32_bf16 v[80:83], v[196:199], v[220:223], v[80:83]
	v_mfma_f32_16x16x32_bf16 v[68:71], v[188:191], v[228:231], v[68:71]
	v_mfma_f32_16x16x32_bf16 v[64:67], v[196:199], v[228:231], v[64:67]
	s_barrier
	s_setprio 0
	s_add_i32 s14, s15, s1
	v_lshl_add_u64 v[180:181], s[38:39], 0, v[128:129]
	s_mov_b32 m0, s14
	ds_read_b128 v[200:203], v151 offset:16384
	ds_read_b128 v[204:207], v151 offset:17408
	ds_read_b128 v[208:211], v151 offset:18432
	ds_read_b128 v[212:215], v151 offset:19456
	ds_read_b128 v[216:219], v151 offset:20480
	ds_read_b128 v[220:223], v151 offset:21504
	ds_read_b128 v[224:227], v151 offset:22528
	ds_read_b128 v[228:231], v151 offset:23552
	global_load_lds_dwordx4 v[180:181], off
	s_add_i32 m0, s14, 0x2000
	s_add_u32 s14, s38, 0x100000
	v_lshl_add_u64 v[182:183], s[38:39], 0, v[138:139]
	s_addc_u32 s15, s39, 0
	s_add_i32 s16, s16, s1
	global_load_lds_dwordx4 v[182:183], off
	v_lshl_add_u64 v[232:233], s[14:15], 0, v[128:129]
	s_mov_b32 m0, s16
	v_lshl_add_u64 v[234:235], s[40:41], 0, v[140:141]
	global_load_lds_dwordx4 v[232:233], off
	v_lshl_add_u64 v[232:233], s[14:15], 0, v[138:139]
	s_add_i32 m0, s16, 0x2000
	s_nop 0
	global_load_lds_dwordx4 v[232:233], off
	v_lshl_add_u64 v[232:233], s[40:41], 0, v[142:143]
	s_mov_b32 m0, s2
	s_nop 0
	global_load_lds_dwordx4 v[232:233], off
	s_mov_b32 m0, s3
	s_nop 0
	global_load_lds_dwordx4 v[234:235], off
	s_waitcnt vmcnt(8) lgkmcnt(0)
	s_setprio 1
	s_barrier
; #define PG8_STAGE(bufoff, gbase, voff) do { _Pragma("unroll") for (int _i = 0; _i < 2; ++_i) \
;         __builtin_amdgcn_global_load_lds((const unsigned*)((const char*)(gbase) + (voff)[_i]), (LAS unsigned*)(lds + (bufoff) + ldsw + _i * 8192), 16, 0, 0); } while (0)
; #define PG8_LDA(dst, b, h) do { _Pragma("unroll") for (int m = 0; m < 4; ++m) _Pragma("unroll") for (int k = 0; k < 2; ++k) dst[m][k] = *(const LAS bf16x8*)(lds + PG8_SA(b, h) + aoff + m * 2048 + k * 1024); } while (0)
; #define PG8_LDB(dst, b, h) do { _Pragma("unroll") for (int n = 0; n < 2; ++n) _Pragma("unroll") for (int k = 0; k < 2; ++k) dst[n][k] = *(const LAS bf16x8*)(lds + PG8_SB(b, h) + boff + n * 2048 + k * 1024); } while (0)
; #define PG8_MMA(ai, bj, At, Bt) do { __builtin_amdgcn_s_setprio(1); _Pragma("unroll") for (int m = 0; m < 4; ++m) _Pragma("unroll") for (int n = 0; n < 2; ++n) _Pragma("unroll") for (int k = 0; k < 2; ++k) \
;         acc[ai][bj][m][n] = __builtin_amdgcn_mfma_f32_16x16x32_bf16(Bt[n][k], At[m][k], acc[ai][bj][m][n], 0, 0, 0); __builtin_amdgcn_s_setprio(0); } while (0)
; #define PG8_WAIT_V(n) asm volatile("s_waitcnt vmcnt(" #n ")" ::: "memory")
; #define PG8_WAIT_L(n) asm volatile("s_waitcnt lgkmcnt(" #n ")" ::: "memory")
; #define PG8_BAR __builtin_amdgcn_s_barrier()
; #define PG8_SCHED __builtin_amdgcn_sched_barrier(0)
; template <class Epi, class Sched>
; __device__ __forceinline__ void gemm_phase(LAS unsigned char* lds, const int K, const Sched& S, const Epi& E) {
;     ...
;             PG8_WAIT_V(8); PG8_WAIT_L(0); PG8_BAR; PG8_MMA(1, 0, At, B0); PG8_MMA(1, 1, At, B1); PG8_BAR; PG8_SCHED;
;             PG8_LDB(B0, 1, 0); PG8_LDB(B1, 1, 1); PG8_SCHED; PG8_LDA(At, 1, 0); PG8_STAGE(PG8_SA(0, 1), a2 + hstep, voffA);
;             PG8_WAIT_V(8); PG8_WAIT_L(0); PG8_BAR; PG8_MMA(0, 0, At, B0); PG8_MMA(0, 1, At, B1); PG8_BAR; PG8_SCHED;
	v_mfma_f32_16x16x32_bf16 v[60:63], v[152:155], v[200:203], v[60:63]
	v_mfma_f32_16x16x32_bf16 v[56:59], v[160:163], v[200:203], v[56:59]
	v_mfma_f32_16x16x32_bf16 v[44:47], v[152:155], v[208:211], v[44:47]
	v_mfma_f32_16x16x32_bf16 v[40:43], v[160:163], v[208:211], v[40:43]
	v_mfma_f32_16x16x32_bf16 v[28:31], v[152:155], v[216:219], v[28:31]
	v_mfma_f32_16x16x32_bf16 v[24:27], v[160:163], v[216:219], v[24:27]
	v_mfma_f32_16x16x32_bf16 v[12:15], v[152:155], v[224:227], v[12:15]
	v_mfma_f32_16x16x32_bf16 v[8:11], v[160:163], v[224:227], v[8:11]
	v_mfma_f32_16x16x32_bf16 v[60:63], v[156:159], v[204:207], v[60:63]
	v_mfma_f32_16x16x32_bf16 v[56:59], v[164:167], v[204:207], v[56:59]
	v_mfma_f32_16x16x32_bf16 v[44:47], v[156:159], v[212:215], v[44:47]
	v_mfma_f32_16x16x32_bf16 v[40:43], v[164:167], v[212:215], v[40:43]
	v_mfma_f32_16x16x32_bf16 v[28:31], v[156:159], v[220:223], v[28:31]
	v_mfma_f32_16x16x32_bf16 v[24:27], v[164:167], v[220:223], v[24:27]
	v_mfma_f32_16x16x32_bf16 v[12:15], v[156:159], v[228:231], v[12:15]
	v_mfma_f32_16x16x32_bf16 v[8:11], v[164:167], v[228:231], v[8:11]
	s_setprio 0
	s_setprio 1
	v_mfma_f32_16x16x32_bf16 v[52:55], v[184:187], v[200:203], v[52:55]
	v_mfma_f32_16x16x32_bf16 v[48:51], v[192:195], v[200:203], v[48:51]
	v_mfma_f32_16x16x32_bf16 v[36:39], v[184:187], v[208:211], v[36:39]
	v_mfma_f32_16x16x32_bf16 v[32:35], v[192:195], v[208:211], v[32:35]
	v_mfma_f32_16x16x32_bf16 v[20:23], v[184:187], v[216:219], v[20:23]
	v_mfma_f32_16x16x32_bf16 v[16:19], v[192:195], v[216:219], v[16:19]
	v_mfma_f32_16x16x32_bf16 v[4:7], v[184:187], v[224:227], v[4:7]
	v_mfma_f32_16x16x32_bf16 v[0:3], v[192:195], v[224:227], v[0:3]
	v_mfma_f32_16x16x32_bf16 v[52:55], v[188:191], v[204:207], v[52:55]
	v_mfma_f32_16x16x32_bf16 v[48:51], v[196:199], v[204:207], v[48:51]
	v_mfma_f32_16x16x32_bf16 v[36:39], v[188:191], v[212:215], v[36:39]
	v_mfma_f32_16x16x32_bf16 v[32:35], v[196:199], v[212:215], v[32:35]
	v_mfma_f32_16x16x32_bf16 v[20:23], v[188:191], v[220:223], v[20:23]
	v_mfma_f32_16x16x32_bf16 v[16:19], v[196:199], v[220:223], v[16:19]
	v_mfma_f32_16x16x32_bf16 v[4:7], v[188:191], v[228:231], v[4:7]
	v_mfma_f32_16x16x32_bf16 v[0:3], v[196:199], v[228:231], v[0:3]
	s_barrier
	s_setprio 0
	s_add_i32 s16, 0, 0x18000
	s_add_i32 s17, 0, 0x1c000
	v_add_u32_e32 v164, s16, v145
	v_add_u32_e32 v196, s17, v145
	ds_read_b128 v[152:155], v164
	ds_read_b128 v[156:159], v164 offset:1024
	ds_read_b128 v[160:163], v164 offset:2048
	ds_read_b128 v[164:167], v164 offset:3072
	ds_read_b128 v[184:187], v196
	ds_read_b128 v[188:191], v196 offset:1024
	ds_read_b128 v[192:195], v196 offset:2048
	ds_read_b128 v[196:199], v196 offset:3072
	s_add_u32 s14, s40, 0x100000
	s_addc_u32 s15, s41, 0
	s_mov_b32 m0, s4
	v_lshl_add_u64 v[236:237], s[14:15], 0, v[142:143]
	ds_read_b128 v[200:203], v151 offset:32768
	ds_read_b128 v[204:207], v151 offset:33792
	ds_read_b128 v[208:211], v151 offset:34816
	ds_read_b128 v[212:215], v151 offset:35840
	ds_read_b128 v[216:219], v151 offset:36864
	ds_read_b128 v[220:223], v151 offset:37888
	ds_read_b128 v[224:227], v151 offset:38912
	ds_read_b128 v[228:231], v151 offset:39936
	global_load_lds_dwordx4 v[236:237], off
	v_lshl_add_u64 v[236:237], s[14:15], 0, v[140:141]
	s_mov_b32 m0, s5
	s_nop 0
	global_load_lds_dwordx4 v[236:237], off
	s_waitcnt vmcnt(8) lgkmcnt(0)
	s_setprio 1
	s_barrier
	v_mfma_f32_16x16x32_bf16 v[124:127], v[152:155], v[200:203], v[124:127]
	v_mfma_f32_16x16x32_bf16 v[120:123], v[160:163], v[200:203], v[120:123]
	v_mfma_f32_16x16x32_bf16 v[108:111], v[152:155], v[208:211], v[108:111]
	v_mfma_f32_16x16x32_bf16 v[104:107], v[160:163], v[208:211], v[104:107]
	v_mfma_f32_16x16x32_bf16 v[92:95], v[152:155], v[216:219], v[92:95]
	v_mfma_f32_16x16x32_bf16 v[88:91], v[160:163], v[216:219], v[88:91]
	v_mfma_f32_16x16x32_bf16 v[76:79], v[152:155], v[224:227], v[76:79]
	v_mfma_f32_16x16x32_bf16 v[72:75], v[160:163], v[224:227], v[72:75]
	v_mfma_f32_16x16x32_bf16 v[124:127], v[156:159], v[204:207], v[124:127]
	v_mfma_f32_16x16x32_bf16 v[120:123], v[164:167], v[204:207], v[120:123]
	v_mfma_f32_16x16x32_bf16 v[108:111], v[156:159], v[212:215], v[108:111]
	v_mfma_f32_16x16x32_bf16 v[104:107], v[164:167], v[212:215], v[104:107]
	v_mfma_f32_16x16x32_bf16 v[92:95], v[156:159], v[220:223], v[92:95]
	v_mfma_f32_16x16x32_bf16 v[88:91], v[164:167], v[220:223], v[88:91]
	v_mfma_f32_16x16x32_bf16 v[76:79], v[156:159], v[228:231], v[76:79]
	v_mfma_f32_16x16x32_bf16 v[72:75], v[164:167], v[228:231], v[72:75]
	s_setprio 0
	s_setprio 1
	v_mfma_f32_16x16x32_bf16 v[116:119], v[184:187], v[200:203], v[116:119]
	v_mfma_f32_16x16x32_bf16 v[112:115], v[192:195], v[200:203], v[112:115]
	v_mfma_f32_16x16x32_bf16 v[100:103], v[184:187], v[208:211], v[100:103]
	v_mfma_f32_16x16x32_bf16 v[96:99], v[192:195], v[208:211], v[96:99]
	v_mfma_f32_16x16x32_bf16 v[84:87], v[184:187], v[216:219], v[84:87]
	v_mfma_f32_16x16x32_bf16 v[80:83], v[192:195], v[216:219], v[80:83]
	v_mfma_f32_16x16x32_bf16 v[68:71], v[184:187], v[224:227], v[68:71]
	v_mfma_f32_16x16x32_bf16 v[64:67], v[192:195], v[224:227], v[64:67]
	v_mfma_f32_16x16x32_bf16 v[116:119], v[188:191], v[204:207], v[116:119]
	v_mfma_f32_16x16x32_bf16 v[112:115], v[196:199], v[204:207], v[112:115]
	v_mfma_f32_16x16x32_bf16 v[100:103], v[188:191], v[212:215], v[100:103]
	v_mfma_f32_16x16x32_bf16 v[96:99], v[196:199], v[212:215], v[96:99]
	v_mfma_f32_16x16x32_bf16 v[84:87], v[188:191], v[220:223], v[84:87]
	v_mfma_f32_16x16x32_bf16 v[80:83], v[196:199], v[220:223], v[80:83]
	v_mfma_f32_16x16x32_bf16 v[68:71], v[188:191], v[228:231], v[68:71]
	v_mfma_f32_16x16x32_bf16 v[64:67], v[196:199], v[228:231], v[64:67]
	s_barrier
; #define PG8_STAGE(bufoff, gbase, voff) do { _Pragma("unroll") for (int _i = 0; _i < 2; ++_i) \
;         __builtin_amdgcn_global_load_lds((const unsigned*)((const char*)(gbase) + (voff)[_i]), (LAS unsigned*)(lds + (bufoff) + ldsw + _i * 8192), 16, 0, 0); } while (0)
; #define PG8_LDA(dst, b, h) do { _Pragma("unroll") for (int m = 0; m < 4; ++m) _Pragma("unroll") for (int k = 0; k < 2; ++k) dst[m][k] = *(const LAS bf16x8*)(lds + PG8_SA(b, h) + aoff + m * 2048 + k * 1024); } while (0)
; #define PG8_MMA(ai, bj, At, Bt) do { __builtin_amdgcn_s_setprio(1); _Pragma("unroll") for (int m = 0; m < 4; ++m) _Pragma("unroll") for (int n = 0; n < 2; ++n) _Pragma("unroll") for (int k = 0; k < 2; ++k) \
;         acc[ai][bj][m][n] = __builtin_amdgcn_mfma_f32_16x16x32_bf16(Bt[n][k], At[m][k], acc[ai][bj][m][n], 0, 0, 0); __builtin_amdgcn_s_setprio(0); } while (0)
; #define PG8_WAIT_V(n) asm volatile("s_waitcnt vmcnt(" #n ")" ::: "memory")
; #define PG8_WAIT_L(n) asm volatile("s_waitcnt lgkmcnt(" #n ")" ::: "memory")
; #define PG8_BAR __builtin_amdgcn_s_barrier()
; #define PG8_SCHED __builtin_amdgcn_sched_barrier(0)
; template <class Epi, class Sched>
; __device__ __forceinline__ void gemm_phase(LAS unsigned char* lds, const int K, const Sched& S, const Epi& E) {
;     ...
;             PG8_LDA(At, 1, 1); PG8_STAGE(PG8_SB(1, 0), b3, voffB); PG8_STAGE(PG8_SB(1, 1), b3 + hstep, voffB); PG8_STAGE(PG8_SA(1, 0), a3, voffA);
;             PG8_WAIT_V(8); PG8_WAIT_L(0); PG8_BAR; PG8_MMA(1, 0, At, B0); PG8_MMA(1, 1, At, B1); PG8_BAR; PG8_SCHED;
;         }
;         if (wr == 0) PG8_BAR;
	s_setprio 0
	s_add_i32 s14, s16, s1
	v_lshl_add_u64 v[180:181], v[180:181], 0, s[36:37]
	s_mov_b32 m0, s14
	ds_read_b128 v[200:203], v151 offset:49152
	ds_read_b128 v[204:207], v151 offset:50176
	ds_read_b128 v[208:211], v151 offset:51200
	ds_read_b128 v[212:215], v151 offset:52224
	ds_read_b128 v[216:219], v151 offset:53248
	ds_read_b128 v[220:223], v151 offset:54272
	ds_read_b128 v[224:227], v151 offset:55296
	ds_read_b128 v[228:231], v151 offset:56320
	global_load_lds_dwordx4 v[180:181], off
	s_add_i32 m0, s14, 0x2000
	s_add_u32 s14, s38, 0x100080
	v_lshl_add_u64 v[180:181], v[182:183], 0, s[36:37]
	s_addc_u32 s15, s39, 0
	s_add_i32 s16, s17, s1
	global_load_lds_dwordx4 v[180:181], off
	v_lshl_add_u64 v[180:181], s[14:15], 0, v[128:129]
	s_mov_b32 m0, s16
	s_nop 0
	global_load_lds_dwordx4 v[180:181], off
	v_lshl_add_u64 v[180:181], s[14:15], 0, v[138:139]
	s_add_i32 m0, s16, 0x2000
	s_nop 0
	global_load_lds_dwordx4 v[180:181], off
	v_lshl_add_u64 v[180:181], v[232:233], 0, s[36:37]
	s_mov_b32 m0, s11
	s_nop 0
	global_load_lds_dwordx4 v[180:181], off
	v_lshl_add_u64 v[180:181], v[234:235], 0, s[36:37]
	s_mov_b32 m0, s12
	s_nop 0
	global_load_lds_dwordx4 v[180:181], off
	s_waitcnt vmcnt(8) lgkmcnt(0)
	s_setprio 1
	s_barrier
	v_mfma_f32_16x16x32_bf16 v[60:63], v[152:155], v[200:203], v[60:63]
	v_mfma_f32_16x16x32_bf16 v[56:59], v[160:163], v[200:203], v[56:59]
	v_mfma_f32_16x16x32_bf16 v[44:47], v[152:155], v[208:211], v[44:47]
	v_mfma_f32_16x16x32_bf16 v[40:43], v[160:163], v[208:211], v[40:43]
	v_mfma_f32_16x16x32_bf16 v[28:31], v[152:155], v[216:219], v[28:31]
	v_mfma_f32_16x16x32_bf16 v[24:27], v[160:163], v[216:219], v[24:27]
	v_mfma_f32_16x16x32_bf16 v[12:15], v[152:155], v[224:227], v[12:15]
	v_mfma_f32_16x16x32_bf16 v[8:11], v[160:163], v[224:227], v[8:11]
	v_mfma_f32_16x16x32_bf16 v[60:63], v[156:159], v[204:207], v[60:63]
	v_mfma_f32_16x16x32_bf16 v[56:59], v[164:167], v[204:207], v[56:59]
	v_mfma_f32_16x16x32_bf16 v[44:47], v[156:159], v[212:215], v[44:47]
	v_mfma_f32_16x16x32_bf16 v[40:43], v[164:167], v[212:215], v[40:43]
	v_mfma_f32_16x16x32_bf16 v[28:31], v[156:159], v[220:223], v[28:31]
	v_mfma_f32_16x16x32_bf16 v[24:27], v[164:167], v[220:223], v[24:27]
	v_mfma_f32_16x16x32_bf16 v[12:15], v[156:159], v[228:231], v[12:15]
	v_mfma_f32_16x16x32_bf16 v[8:11], v[164:167], v[228:231], v[8:11]
	s_setprio 0
	s_setprio 1
	v_mfma_f32_16x16x32_bf16 v[52:55], v[184:187], v[200:203], v[52:55]
	v_mfma_f32_16x16x32_bf16 v[48:51], v[192:195], v[200:203], v[48:51]
	v_mfma_f32_16x16x32_bf16 v[36:39], v[184:187], v[208:211], v[36:39]
	v_mfma_f32_16x16x32_bf16 v[32:35], v[192:195], v[208:211], v[32:35]
	v_mfma_f32_16x16x32_bf16 v[20:23], v[184:187], v[216:219], v[20:23]
	v_mfma_f32_16x16x32_bf16 v[16:19], v[192:195], v[216:219], v[16:19]
	v_mfma_f32_16x16x32_bf16 v[4:7], v[184:187], v[224:227], v[4:7]
	v_mfma_f32_16x16x32_bf16 v[0:3], v[192:195], v[224:227], v[0:3]
	v_mfma_f32_16x16x32_bf16 v[52:55], v[188:191], v[204:207], v[52:55]
	v_mfma_f32_16x16x32_bf16 v[48:51], v[196:199], v[204:207], v[48:51]
	v_mfma_f32_16x16x32_bf16 v[36:39], v[188:191], v[212:215], v[36:39]
	v_mfma_f32_16x16x32_bf16 v[32:35], v[196:199], v[212:215], v[32:35]
	v_mfma_f32_16x16x32_bf16 v[20:23], v[188:191], v[220:223], v[20:23]
	v_mfma_f32_16x16x32_bf16 v[16:19], v[196:199], v[220:223], v[16:19]
	v_mfma_f32_16x16x32_bf16 v[4:7], v[188:191], v[228:231], v[4:7]
	v_mfma_f32_16x16x32_bf16 v[0:3], v[196:199], v[228:231], v[0:3]
	s_barrier
	s_setprio 0
	s_add_i32 s13, s13, 2
	s_add_u32 s8, s8, 0x100
	s_addc_u32 s9, s9, 0
	s_cmp_gt_u32 s13, 61
	s_cbranch_scc0 .LBB0_511
	s_cmpk_lt_u32 s0, 0x100
	s_cbranch_scc0 .LBB0_514
	s_barrier

; #define PG8_STAGE(bufoff, gbase, voff) do { _Pragma("unroll") for (int _i = 0; _i < 2; ++_i) \
;         __builtin_amdgcn_global_load_lds((const unsigned*)((const char*)(gbase) + (voff)[_i]), (LAS unsigned*)(lds + (bufoff) + ldsw + _i * 8192), 16, 0, 0); } while (0)
; #define PG8_LDA(dst, b, h) do { _Pragma("unroll") for (int m = 0; m < 4; ++m) _Pragma("unroll") for (int k = 0; k < 2; ++k) dst[m][k] = *(const LAS bf16x8*)(lds + PG8_SA(b, h) + aoff + m * 2048 + k * 1024); } while (0)
; #define PG8_LDB(dst, b, h) do { _Pragma("unroll") for (int n = 0; n < 2; ++n) _Pragma("unroll") for (int k = 0; k < 2; ++k) dst[n][k] = *(const LAS bf16x8*)(lds + PG8_SB(b, h) + boff + n * 2048 + k * 1024); } while (0)
; #define PG8_MMA(ai, bj, At, Bt) do { __builtin_amdgcn_s_setprio(1); _Pragma("unroll") for (int m = 0; m < 4; ++m) _Pragma("unroll") for (int n = 0; n < 2; ++n) _Pragma("unroll") for (int k = 0; k < 2; ++k) \
;         acc[ai][bj][m][n] = __builtin_amdgcn_mfma_f32_16x16x32_bf16(Bt[n][k], At[m][k], acc[ai][bj][m][n], 0, 0, 0); __builtin_amdgcn_s_setprio(0); } while (0)
; #define PG8_WAIT_V(n) asm volatile("s_waitcnt vmcnt(" #n ")" ::: "memory")
; #define PG8_WAIT_L(n) asm volatile("s_waitcnt lgkmcnt(" #n ")" ::: "memory")
; #define PG8_BAR __builtin_amdgcn_s_barrier()
; #define PG8_SCHED __builtin_amdgcn_sched_barrier(0)
; template <class Epi, class Sched>
; __device__ __forceinline__ void gemm_phase(LAS unsigned char* lds, const int K, const Sched& S, const Epi& E) {
;     ...
;         for (int t = 0; t < nt; t += 2) {
;             const bool last = (t == nt - 2);
;             const char* a1 = cA + (size_t)(t + 1) * kstep;
;             const char* a2 = last ? nA : cA + (size_t)(t + 2) * kstep; const char* b2 = last ? nB : cB + (size_t)(t + 2) * kstep;
;             const char* a3 = a2 + kstep; const char* b3 = b2 + kstep;
;             PG8_LDB(B0, 0, 0); PG8_LDB(B1, 0, 1); PG8_SCHED; PG8_LDA(At, 0, 0); PG8_STAGE(PG8_SA(1, 1), a1 + hstep, voffA);
;             PG8_WAIT_V(8); PG8_WAIT_L(0); PG8_BAR; PG8_MMA(0, 0, At, B0); PG8_MMA(0, 1, At, B1); PG8_BAR; PG8_SCHED;
;             PG8_LDA(At, 0, 1); PG8_STAGE(PG8_SB(0, 0), b2, voffB); PG8_STAGE(PG8_SB(0, 1), b2 + hstep, voffB); PG8_STAGE(PG8_SA(0, 0), a2, voffA);
;             PG8_WAIT_V(8); PG8_WAIT_L(0); PG8_BAR; PG8_MMA(1, 0, At, B0); PG8_MMA(1, 1, At, B1); PG8_BAR; PG8_SCHED;
.LBB0_533:
	s_add_u32 s14, s50, s11
	s_addc_u32 s15, s51, 0
	s_add_u32 s16, s14, 0x100
	s_addc_u32 s17, s15, 0
	s_and_b64 s[12:13], s[54:55], exec
	s_cselect_b32 s59, s45, s17
	s_cselect_b32 s58, s44, s16
	s_add_u32 s11, s8, s11
	s_addc_u32 s12, s9, 0
	s_add_u32 s11, s11, 0x100
	s_addc_u32 s16, s12, 0
	s_add_i32 s21, 0, 0x10000
	s_and_b64 s[12:13], s[54:55], exec
	s_cselect_b32 s61, s47, s16
	s_cselect_b32 s60, s46, s11
	s_add_i32 s25, 0, 0x14000
	s_add_u32 s64, s14, 0x10080
	s_addc_u32 s65, s15, 0
	s_add_i32 s19, s21, s3
	s_add_i32 m0, s26, 0xc000
	s_add_i32 s28, s26, 0xe000
	s_add_i32 s15, s19, 0x2000
	v_add_u32_e32 v146, s21, v148
	s_add_u32 s62, s60, 0x10000
	ds_read_b128 v[152:155], v146
	ds_read_b128 v[156:159], v146 offset:1024
	ds_read_b128 v[160:163], v146 offset:2048
	ds_read_b128 v[164:167], v146 offset:3072
	v_add_u32_e32 v146, s25, v148
	s_addc_u32 s63, s61, 0
	s_add_i32 s17, s25, s3
	ds_read_b128 v[184:187], v146
	ds_read_b128 v[188:191], v146 offset:1024
	ds_read_b128 v[192:195], v146 offset:2048
	ds_read_b128 v[196:199], v146 offset:3072
	s_add_i32 s16, s17, 0x2000
	s_add_i32 s14, 0, 0x18000
	s_add_i32 s13, 0, 0x1c000
	s_add_u32 s56, s58, 0x10000
	s_addc_u32 s57, s59, 0
	s_add_i32 s12, s14, s3
	s_add_i32 s11, s12, 0x2000
	s_add_u32 s54, s60, 0x10080
	s_addc_u32 s55, s61, 0
	s_add_i32 s25, s13, s3
	s_add_i32 s21, s25, 0x2000
	v_lshl_add_u64 v[146:147], s[64:65], 0, v[144:145]
	ds_read_b128 v[200:203], v150
	ds_read_b128 v[204:207], v150 offset:1024
	ds_read_b128 v[208:211], v150 offset:2048
	ds_read_b128 v[212:215], v150 offset:3072
	ds_read_b128 v[216:219], v150 offset:4096
	ds_read_b128 v[220:223], v150 offset:5120
	ds_read_b128 v[224:227], v150 offset:6144
	ds_read_b128 v[228:231], v150 offset:7168
	global_load_lds_dwordx4 v[146:147], off
	v_lshl_add_u64 v[146:147], s[64:65], 0, v[140:141]
	s_mov_b32 m0, s28
	s_nop 0
	global_load_lds_dwordx4 v[146:147], off
	s_waitcnt vmcnt(8) lgkmcnt(0)
	s_setprio 1
	s_barrier
	v_mfma_f32_16x16x32_bf16 v[124:127], v[152:155], v[200:203], v[124:127]
	v_mfma_f32_16x16x32_bf16 v[120:123], v[160:163], v[200:203], v[120:123]
	v_mfma_f32_16x16x32_bf16 v[112:115], v[152:155], v[208:211], v[112:115]
	v_mfma_f32_16x16x32_bf16 v[104:107], v[160:163], v[208:211], v[104:107]
	v_mfma_f32_16x16x32_bf16 v[96:99], v[152:155], v[216:219], v[96:99]
	v_mfma_f32_16x16x32_bf16 v[88:91], v[160:163], v[216:219], v[88:91]
	v_mfma_f32_16x16x32_bf16 v[80:83], v[152:155], v[224:227], v[80:83]
	v_mfma_f32_16x16x32_bf16 v[72:75], v[160:163], v[224:227], v[72:75]
	v_mfma_f32_16x16x32_bf16 v[124:127], v[156:159], v[204:207], v[124:127]
	v_mfma_f32_16x16x32_bf16 v[120:123], v[164:167], v[204:207], v[120:123]
	v_mfma_f32_16x16x32_bf16 v[112:115], v[156:159], v[212:215], v[112:115]
	v_mfma_f32_16x16x32_bf16 v[104:107], v[164:167], v[212:215], v[104:107]
	v_mfma_f32_16x16x32_bf16 v[96:99], v[156:159], v[220:223], v[96:99]
	v_mfma_f32_16x16x32_bf16 v[88:91], v[164:167], v[220:223], v[88:91]
	v_mfma_f32_16x16x32_bf16 v[80:83], v[156:159], v[228:231], v[80:83]
	v_mfma_f32_16x16x32_bf16 v[72:75], v[164:167], v[228:231], v[72:75]
	s_setprio 0
	s_setprio 1
	v_mfma_f32_16x16x32_bf16 v[116:119], v[184:187], v[200:203], v[116:119]
	v_mfma_f32_16x16x32_bf16 v[108:111], v[192:195], v[200:203], v[108:111]
	v_mfma_f32_16x16x32_bf16 v[100:103], v[184:187], v[208:211], v[100:103]
	v_mfma_f32_16x16x32_bf16 v[92:95], v[192:195], v[208:211], v[92:95]
	v_mfma_f32_16x16x32_bf16 v[84:87], v[184:187], v[216:219], v[84:87]
	v_mfma_f32_16x16x32_bf16 v[76:79], v[192:195], v[216:219], v[76:79]
	v_mfma_f32_16x16x32_bf16 v[68:71], v[184:187], v[224:227], v[68:71]
	v_mfma_f32_16x16x32_bf16 v[64:67], v[192:195], v[224:227], v[64:67]
	v_mfma_f32_16x16x32_bf16 v[116:119], v[188:191], v[204:207], v[116:119]
	v_mfma_f32_16x16x32_bf16 v[108:111], v[196:199], v[204:207], v[108:111]
	v_mfma_f32_16x16x32_bf16 v[100:103], v[188:191], v[212:215], v[100:103]
	v_mfma_f32_16x16x32_bf16 v[92:95], v[196:199], v[212:215], v[92:95]
	v_mfma_f32_16x16x32_bf16 v[84:87], v[188:191], v[220:223], v[84:87]
	v_mfma_f32_16x16x32_bf16 v[76:79], v[196:199], v[220:223], v[76:79]
	v_mfma_f32_16x16x32_bf16 v[68:71], v[188:191], v[228:231], v[68:71]
	v_mfma_f32_16x16x32_bf16 v[64:67], v[196:199], v[228:231], v[64:67]
	s_barrier
	s_setprio 0
	s_mov_b32 m0, s19
	v_lshl_add_u64 v[146:147], s[60:61], 0, v[142:143]
	ds_read_b128 v[200:203], v150 offset:16384
	ds_read_b128 v[204:207], v150 offset:17408
	ds_read_b128 v[208:211], v150 offset:18432
	ds_read_b128 v[212:215], v150 offset:19456
	ds_read_b128 v[216:219], v150 offset:20480
	ds_read_b128 v[220:223], v150 offset:21504
	ds_read_b128 v[224:227], v150 offset:22528
	ds_read_b128 v[228:231], v150 offset:23552
	global_load_lds_dwordx4 v[146:147], off
	v_lshl_add_u64 v[180:181], s[60:61], 0, v[138:139]
	s_mov_b32 m0, s15
	v_lshl_add_u64 v[182:183], s[62:63], 0, v[142:143]
	global_load_lds_dwordx4 v[180:181], off
	s_mov_b32 m0, s17
	v_lshl_add_u64 v[232:233], s[58:59], 0, v[140:141]
	global_load_lds_dwordx4 v[182:183], off
	v_lshl_add_u64 v[182:183], s[62:63], 0, v[138:139]
	s_mov_b32 m0, s16
	s_nop 0
	global_load_lds_dwordx4 v[182:183], off
	v_lshl_add_u64 v[182:183], s[58:59], 0, v[144:145]
	s_mov_b32 m0, s26
	s_nop 0
	global_load_lds_dwordx4 v[182:183], off
	s_mov_b32 m0, s27
	s_nop 0
	global_load_lds_dwordx4 v[232:233], off
	s_waitcnt vmcnt(8) lgkmcnt(0)
	s_setprio 1
	s_barrier
; #define PG8_STAGE(bufoff, gbase, voff) do { _Pragma("unroll") for (int _i = 0; _i < 2; ++_i) \
;         __builtin_amdgcn_global_load_lds((const unsigned*)((const char*)(gbase) + (voff)[_i]), (LAS unsigned*)(lds + (bufoff) + ldsw + _i * 8192), 16, 0, 0); } while (0)
; #define PG8_LDA(dst, b, h) do { _Pragma("unroll") for (int m = 0; m < 4; ++m) _Pragma("unroll") for (int k = 0; k < 2; ++k) dst[m][k] = *(const LAS bf16x8*)(lds + PG8_SA(b, h) + aoff + m * 2048 + k * 1024); } while (0)
; #define PG8_LDB(dst, b, h) do { _Pragma("unroll") for (int n = 0; n < 2; ++n) _Pragma("unroll") for (int k = 0; k < 2; ++k) dst[n][k] = *(const LAS bf16x8*)(lds + PG8_SB(b, h) + boff + n * 2048 + k * 1024); } while (0)
; #define PG8_MMA(ai, bj, At, Bt) do { __builtin_amdgcn_s_setprio(1); _Pragma("unroll") for (int m = 0; m < 4; ++m) _Pragma("unroll") for (int n = 0; n < 2; ++n) _Pragma("unroll") for (int k = 0; k < 2; ++k) \
;         acc[ai][bj][m][n] = __builtin_amdgcn_mfma_f32_16x16x32_bf16(Bt[n][k], At[m][k], acc[ai][bj][m][n], 0, 0, 0); __builtin_amdgcn_s_setprio(0); } while (0)
; #define PG8_WAIT_V(n) asm volatile("s_waitcnt vmcnt(" #n ")" ::: "memory")
; #define PG8_WAIT_L(n) asm volatile("s_waitcnt lgkmcnt(" #n ")" ::: "memory")
; #define PG8_BAR __builtin_amdgcn_s_barrier()
; #define PG8_SCHED __builtin_amdgcn_sched_barrier(0)
; template <class Epi, class Sched>
; __device__ __forceinline__ void gemm_phase(LAS unsigned char* lds, const int K, const Sched& S, const Epi& E) {
;     ...
;             PG8_WAIT_V(8); PG8_WAIT_L(0); PG8_BAR; PG8_MMA(1, 0, At, B0); PG8_MMA(1, 1, At, B1); PG8_BAR; PG8_SCHED;
;             PG8_LDB(B0, 1, 0); PG8_LDB(B1, 1, 1); PG8_SCHED; PG8_LDA(At, 1, 0); PG8_STAGE(PG8_SA(0, 1), a2 + hstep, voffA);
;             PG8_WAIT_V(8); PG8_WAIT_L(0); PG8_BAR; PG8_MMA(0, 0, At, B0); PG8_MMA(0, 1, At, B1); PG8_BAR; PG8_SCHED;
	v_mfma_f32_16x16x32_bf16 v[60:63], v[152:155], v[200:203], v[60:63]
	v_mfma_f32_16x16x32_bf16 v[56:59], v[160:163], v[200:203], v[56:59]
	v_mfma_f32_16x16x32_bf16 v[48:51], v[152:155], v[208:211], v[48:51]
	v_mfma_f32_16x16x32_bf16 v[40:43], v[160:163], v[208:211], v[40:43]
	v_mfma_f32_16x16x32_bf16 v[32:35], v[152:155], v[216:219], v[32:35]
	v_mfma_f32_16x16x32_bf16 v[24:27], v[160:163], v[216:219], v[24:27]
	v_mfma_f32_16x16x32_bf16 v[16:19], v[152:155], v[224:227], v[16:19]
	v_mfma_f32_16x16x32_bf16 v[8:11], v[160:163], v[224:227], v[8:11]
	v_mfma_f32_16x16x32_bf16 v[60:63], v[156:159], v[204:207], v[60:63]
	v_mfma_f32_16x16x32_bf16 v[56:59], v[164:167], v[204:207], v[56:59]
	v_mfma_f32_16x16x32_bf16 v[48:51], v[156:159], v[212:215], v[48:51]
	v_mfma_f32_16x16x32_bf16 v[40:43], v[164:167], v[212:215], v[40:43]
	v_mfma_f32_16x16x32_bf16 v[32:35], v[156:159], v[220:223], v[32:35]
	v_mfma_f32_16x16x32_bf16 v[24:27], v[164:167], v[220:223], v[24:27]
	v_mfma_f32_16x16x32_bf16 v[16:19], v[156:159], v[228:231], v[16:19]
	v_mfma_f32_16x16x32_bf16 v[8:11], v[164:167], v[228:231], v[8:11]
	s_setprio 0
	s_setprio 1
	v_mfma_f32_16x16x32_bf16 v[52:55], v[184:187], v[200:203], v[52:55]
	v_mfma_f32_16x16x32_bf16 v[44:47], v[192:195], v[200:203], v[44:47]
	v_mfma_f32_16x16x32_bf16 v[36:39], v[184:187], v[208:211], v[36:39]
	v_mfma_f32_16x16x32_bf16 v[28:31], v[192:195], v[208:211], v[28:31]
	v_mfma_f32_16x16x32_bf16 v[20:23], v[184:187], v[216:219], v[20:23]
	v_mfma_f32_16x16x32_bf16 v[12:15], v[192:195], v[216:219], v[12:15]
	v_mfma_f32_16x16x32_bf16 v[4:7], v[184:187], v[224:227], v[4:7]
	v_mfma_f32_16x16x32_bf16 v[0:3], v[192:195], v[224:227], v[0:3]
	v_mfma_f32_16x16x32_bf16 v[52:55], v[188:191], v[204:207], v[52:55]
	v_mfma_f32_16x16x32_bf16 v[44:47], v[196:199], v[204:207], v[44:47]
	v_mfma_f32_16x16x32_bf16 v[36:39], v[188:191], v[212:215], v[36:39]
	v_mfma_f32_16x16x32_bf16 v[28:31], v[196:199], v[212:215], v[28:31]
	v_mfma_f32_16x16x32_bf16 v[20:23], v[188:191], v[220:223], v[20:23]
	v_mfma_f32_16x16x32_bf16 v[12:15], v[196:199], v[220:223], v[12:15]
	v_mfma_f32_16x16x32_bf16 v[4:7], v[188:191], v[228:231], v[4:7]
	v_mfma_f32_16x16x32_bf16 v[0:3], v[196:199], v[228:231], v[0:3]
	s_barrier
	s_setprio 0
	v_add_u32_e32 v151, s14, v148
	ds_read_b128 v[152:155], v151
	ds_read_b128 v[156:159], v151 offset:1024
	ds_read_b128 v[160:163], v151 offset:2048
	ds_read_b128 v[164:167], v151 offset:3072
	v_add_u32_e32 v151, s13, v148
	ds_read_b128 v[184:187], v151
	ds_read_b128 v[188:191], v151 offset:1024
	ds_read_b128 v[192:195], v151 offset:2048
	ds_read_b128 v[196:199], v151 offset:3072
	s_mov_b32 m0, s66
	v_lshl_add_u64 v[234:235], s[56:57], 0, v[144:145]
	ds_read_b128 v[200:203], v150 offset:32768
	ds_read_b128 v[204:207], v150 offset:33792
	ds_read_b128 v[208:211], v150 offset:34816
	ds_read_b128 v[212:215], v150 offset:35840
	ds_read_b128 v[216:219], v150 offset:36864
	ds_read_b128 v[220:223], v150 offset:37888
	ds_read_b128 v[224:227], v150 offset:38912
	ds_read_b128 v[228:231], v150 offset:39936
	global_load_lds_dwordx4 v[234:235], off
	v_lshl_add_u64 v[234:235], s[56:57], 0, v[140:141]
	s_mov_b32 m0, s67
	s_nop 0
	global_load_lds_dwordx4 v[234:235], off
	s_waitcnt vmcnt(8) lgkmcnt(0)
	s_setprio 1
	s_barrier
	v_mfma_f32_16x16x32_bf16 v[124:127], v[152:155], v[200:203], v[124:127]
	v_mfma_f32_16x16x32_bf16 v[120:123], v[160:163], v[200:203], v[120:123]
	v_mfma_f32_16x16x32_bf16 v[112:115], v[152:155], v[208:211], v[112:115]
	v_mfma_f32_16x16x32_bf16 v[104:107], v[160:163], v[208:211], v[104:107]
	v_mfma_f32_16x16x32_bf16 v[96:99], v[152:155], v[216:219], v[96:99]
	v_mfma_f32_16x16x32_bf16 v[88:91], v[160:163], v[216:219], v[88:91]
	v_mfma_f32_16x16x32_bf16 v[80:83], v[152:155], v[224:227], v[80:83]
	v_mfma_f32_16x16x32_bf16 v[72:75], v[160:163], v[224:227], v[72:75]
	v_mfma_f32_16x16x32_bf16 v[124:127], v[156:159], v[204:207], v[124:127]
	v_mfma_f32_16x16x32_bf16 v[120:123], v[164:167], v[204:207], v[120:123]
	v_mfma_f32_16x16x32_bf16 v[112:115], v[156:159], v[212:215], v[112:115]
	v_mfma_f32_16x16x32_bf16 v[104:107], v[164:167], v[212:215], v[104:107]
	v_mfma_f32_16x16x32_bf16 v[96:99], v[156:159], v[220:223], v[96:99]
	v_mfma_f32_16x16x32_bf16 v[88:91], v[164:167], v[220:223], v[88:91]
	v_mfma_f32_16x16x32_bf16 v[80:83], v[156:159], v[228:231], v[80:83]
	v_mfma_f32_16x16x32_bf16 v[72:75], v[164:167], v[228:231], v[72:75]
	s_setprio 0
	s_setprio 1
	v_mfma_f32_16x16x32_bf16 v[116:119], v[184:187], v[200:203], v[116:119]
	v_mfma_f32_16x16x32_bf16 v[108:111], v[192:195], v[200:203], v[108:111]
	v_mfma_f32_16x16x32_bf16 v[100:103], v[184:187], v[208:211], v[100:103]
	v_mfma_f32_16x16x32_bf16 v[92:95], v[192:195], v[208:211], v[92:95]
	v_mfma_f32_16x16x32_bf16 v[84:87], v[184:187], v[216:219], v[84:87]
	v_mfma_f32_16x16x32_bf16 v[76:79], v[192:195], v[216:219], v[76:79]
	v_mfma_f32_16x16x32_bf16 v[68:71], v[184:187], v[224:227], v[68:71]
	v_mfma_f32_16x16x32_bf16 v[64:67], v[192:195], v[224:227], v[64:67]
	v_mfma_f32_16x16x32_bf16 v[116:119], v[188:191], v[204:207], v[116:119]
	v_mfma_f32_16x16x32_bf16 v[108:111], v[196:199], v[204:207], v[108:111]
	v_mfma_f32_16x16x32_bf16 v[100:103], v[188:191], v[212:215], v[100:103]
	v_mfma_f32_16x16x32_bf16 v[92:95], v[196:199], v[212:215], v[92:95]
	v_mfma_f32_16x16x32_bf16 v[84:87], v[188:191], v[220:223], v[84:87]
	v_mfma_f32_16x16x32_bf16 v[76:79], v[196:199], v[220:223], v[76:79]
	v_mfma_f32_16x16x32_bf16 v[68:71], v[188:191], v[228:231], v[68:71]
	v_mfma_f32_16x16x32_bf16 v[64:67], v[196:199], v[228:231], v[64:67]
	s_barrier
; #define PG8_STAGE(bufoff, gbase, voff) do { _Pragma("unroll") for (int _i = 0; _i < 2; ++_i) \
;         __builtin_amdgcn_global_load_lds((const unsigned*)((const char*)(gbase) + (voff)[_i]), (LAS unsigned*)(lds + (bufoff) + ldsw + _i * 8192), 16, 0, 0); } while (0)
; #define PG8_LDA(dst, b, h) do { _Pragma("unroll") for (int m = 0; m < 4; ++m) _Pragma("unroll") for (int k = 0; k < 2; ++k) dst[m][k] = *(const LAS bf16x8*)(lds + PG8_SA(b, h) + aoff + m * 2048 + k * 1024); } while (0)
; #define PG8_MMA(ai, bj, At, Bt) do { __builtin_amdgcn_s_setprio(1); _Pragma("unroll") for (int m = 0; m < 4; ++m) _Pragma("unroll") for (int n = 0; n < 2; ++n) _Pragma("unroll") for (int k = 0; k < 2; ++k) \
;         acc[ai][bj][m][n] = __builtin_amdgcn_mfma_f32_16x16x32_bf16(Bt[n][k], At[m][k], acc[ai][bj][m][n], 0, 0, 0); __builtin_amdgcn_s_setprio(0); } while (0)
; #define PG8_WAIT_V(n) asm volatile("s_waitcnt vmcnt(" #n ")" ::: "memory")
; #define PG8_WAIT_L(n) asm volatile("s_waitcnt lgkmcnt(" #n ")" ::: "memory")
; #define PG8_BAR __builtin_amdgcn_s_barrier()
; #define PG8_SCHED __builtin_amdgcn_sched_barrier(0)
; template <class Epi, class Sched>
; __device__ __forceinline__ void gemm_phase(LAS unsigned char* lds, const int K, const Sched& S, const Epi& E) {
;     ...
;             PG8_LDA(At, 1, 1); PG8_STAGE(PG8_SB(1, 0), b3, voffB); PG8_STAGE(PG8_SB(1, 1), b3 + hstep, voffB); PG8_STAGE(PG8_SA(1, 0), a3, voffA);
;             PG8_WAIT_V(8); PG8_WAIT_L(0); PG8_BAR; PG8_MMA(1, 0, At, B0); PG8_MMA(1, 1, At, B1); PG8_BAR; PG8_SCHED;
;         }
;         if (wr == 0) PG8_BAR;
	s_setprio 0
	s_mov_b32 m0, s12
	v_lshl_add_u64 v[146:147], v[146:147], 0, s[36:37]
	ds_read_b128 v[200:203], v150 offset:49152
	ds_read_b128 v[204:207], v150 offset:50176
	ds_read_b128 v[208:211], v150 offset:51200
	ds_read_b128 v[212:215], v150 offset:52224
	ds_read_b128 v[216:219], v150 offset:53248
	ds_read_b128 v[220:223], v150 offset:54272
	ds_read_b128 v[224:227], v150 offset:55296
	ds_read_b128 v[228:231], v150 offset:56320
	global_load_lds_dwordx4 v[146:147], off
	v_lshl_add_u64 v[146:147], v[180:181], 0, s[36:37]
	s_mov_b32 m0, s11
	s_nop 0
	global_load_lds_dwordx4 v[146:147], off
	v_lshl_add_u64 v[146:147], s[54:55], 0, v[142:143]
	s_mov_b32 m0, s25
	s_nop 0
	global_load_lds_dwordx4 v[146:147], off
	v_lshl_add_u64 v[146:147], s[54:55], 0, v[138:139]
	s_mov_b32 m0, s21
	s_nop 0
	global_load_lds_dwordx4 v[146:147], off
	v_lshl_add_u64 v[146:147], v[182:183], 0, s[36:37]
	s_mov_b32 m0, s0
	s_nop 0
	global_load_lds_dwordx4 v[146:147], off
	v_lshl_add_u64 v[146:147], v[232:233], 0, s[36:37]
	s_mov_b32 m0, s1
	s_nop 0
	global_load_lds_dwordx4 v[146:147], off
	s_waitcnt vmcnt(8) lgkmcnt(0)
	s_setprio 1
	s_barrier
	v_mfma_f32_16x16x32_bf16 v[60:63], v[152:155], v[200:203], v[60:63]
	v_mfma_f32_16x16x32_bf16 v[56:59], v[160:163], v[200:203], v[56:59]
	v_mfma_f32_16x16x32_bf16 v[48:51], v[152:155], v[208:211], v[48:51]
	v_mfma_f32_16x16x32_bf16 v[40:43], v[160:163], v[208:211], v[40:43]
	v_mfma_f32_16x16x32_bf16 v[32:35], v[152:155], v[216:219], v[32:35]
	v_mfma_f32_16x16x32_bf16 v[24:27], v[160:163], v[216:219], v[24:27]
	v_mfma_f32_16x16x32_bf16 v[16:19], v[152:155], v[224:227], v[16:19]
	v_mfma_f32_16x16x32_bf16 v[8:11], v[160:163], v[224:227], v[8:11]
	v_mfma_f32_16x16x32_bf16 v[60:63], v[156:159], v[204:207], v[60:63]
	v_mfma_f32_16x16x32_bf16 v[56:59], v[164:167], v[204:207], v[56:59]
	v_mfma_f32_16x16x32_bf16 v[48:51], v[156:159], v[212:215], v[48:51]
	v_mfma_f32_16x16x32_bf16 v[40:43], v[164:167], v[212:215], v[40:43]
	v_mfma_f32_16x16x32_bf16 v[32:35], v[156:159], v[220:223], v[32:35]
	v_mfma_f32_16x16x32_bf16 v[24:27], v[164:167], v[220:223], v[24:27]
	v_mfma_f32_16x16x32_bf16 v[16:19], v[156:159], v[228:231], v[16:19]
	v_mfma_f32_16x16x32_bf16 v[8:11], v[164:167], v[228:231], v[8:11]
	s_setprio 0
	s_setprio 1
	v_mfma_f32_16x16x32_bf16 v[52:55], v[184:187], v[200:203], v[52:55]
	v_mfma_f32_16x16x32_bf16 v[44:47], v[192:195], v[200:203], v[44:47]
	v_mfma_f32_16x16x32_bf16 v[36:39], v[184:187], v[208:211], v[36:39]
	v_mfma_f32_16x16x32_bf16 v[28:31], v[192:195], v[208:211], v[28:31]
	v_mfma_f32_16x16x32_bf16 v[20:23], v[184:187], v[216:219], v[20:23]
	v_mfma_f32_16x16x32_bf16 v[12:15], v[192:195], v[216:219], v[12:15]
	v_mfma_f32_16x16x32_bf16 v[4:7], v[184:187], v[224:227], v[4:7]
	v_mfma_f32_16x16x32_bf16 v[0:3], v[192:195], v[224:227], v[0:3]
	v_mfma_f32_16x16x32_bf16 v[52:55], v[188:191], v[204:207], v[52:55]
	v_mfma_f32_16x16x32_bf16 v[44:47], v[196:199], v[204:207], v[44:47]
	v_mfma_f32_16x16x32_bf16 v[36:39], v[188:191], v[212:215], v[36:39]
	v_mfma_f32_16x16x32_bf16 v[28:31], v[196:199], v[212:215], v[28:31]
	v_mfma_f32_16x16x32_bf16 v[20:23], v[188:191], v[220:223], v[20:23]
	v_mfma_f32_16x16x32_bf16 v[12:15], v[196:199], v[220:223], v[12:15]
	v_mfma_f32_16x16x32_bf16 v[4:7], v[188:191], v[228:231], v[4:7]
	v_mfma_f32_16x16x32_bf16 v[0:3], v[196:199], v[228:231], v[0:3]
	s_barrier
	s_setprio 0
	s_movk_i32 s11, 0x100
	s_andn2_b64 vcc, exec, s[52:53]
	s_mov_b64 s[54:55], -1
	s_mov_b64 s[52:53], 0
	s_cbranch_vccz .LBB0_533
	s_and_b64 vcc, exec, s[40:41]
	s_cbranch_vccz .LBB0_536
	s_barrier

; #define PG8_STAGE(bufoff, gbase, voff) do { _Pragma("unroll") for (int _i = 0; _i < 2; ++_i) \
;         __builtin_amdgcn_global_load_lds((const unsigned*)((const char*)(gbase) + (voff)[_i]), (LAS unsigned*)(lds + (bufoff) + ldsw + _i * 8192), 16, 0, 0); } while (0)
; #define PG8_LDA(dst, b, h) do { _Pragma("unroll") for (int m = 0; m < 4; ++m) _Pragma("unroll") for (int k = 0; k < 2; ++k) dst[m][k] = *(const LAS bf16x8*)(lds + PG8_SA(b, h) + aoff + m * 2048 + k * 1024); } while (0)
; #define PG8_LDB(dst, b, h) do { _Pragma("unroll") for (int n = 0; n < 2; ++n) _Pragma("unroll") for (int k = 0; k < 2; ++k) dst[n][k] = *(const LAS bf16x8*)(lds + PG8_SB(b, h) + boff + n * 2048 + k * 1024); } while (0)
; #define PG8_MMA(ai, bj, At, Bt) do { __builtin_amdgcn_s_setprio(1); _Pragma("unroll") for (int m = 0; m < 4; ++m) _Pragma("unroll") for (int n = 0; n < 2; ++n) _Pragma("unroll") for (int k = 0; k < 2; ++k) \
;         acc[ai][bj][m][n] = __builtin_amdgcn_mfma_f32_16x16x32_bf16(Bt[n][k], At[m][k], acc[ai][bj][m][n], 0, 0, 0); __builtin_amdgcn_s_setprio(0); } while (0)
; #define PG8_WAIT_V(n) asm volatile("s_waitcnt vmcnt(" #n ")" ::: "memory")
; #define PG8_WAIT_L(n) asm volatile("s_waitcnt lgkmcnt(" #n ")" ::: "memory")
; #define PG8_BAR __builtin_amdgcn_s_barrier()
; #define PG8_SCHED __builtin_amdgcn_sched_barrier(0)
; template <class Epi, class Sched>
; __device__ __forceinline__ void gemm_phase(LAS unsigned char* lds, const int K, const Sched& S, const Epi& E) {
;     ...
;         for (int t = 0; t < nt; t += 2) {
;             const bool last = (t == nt - 2);
;             const char* a1 = cA + (size_t)(t + 1) * kstep;
;             const char* a2 = last ? nA : cA + (size_t)(t + 2) * kstep; const char* b2 = last ? nB : cB + (size_t)(t + 2) * kstep;
;             const char* a3 = a2 + kstep; const char* b3 = b2 + kstep;
;             PG8_LDB(B0, 0, 0); PG8_LDB(B1, 0, 1); PG8_SCHED; PG8_LDA(At, 0, 0); PG8_STAGE(PG8_SA(1, 1), a1 + hstep, voffA);
;             PG8_WAIT_V(8); PG8_WAIT_L(0); PG8_BAR; PG8_MMA(0, 0, At, B0); PG8_MMA(0, 1, At, B1); PG8_BAR; PG8_SCHED;
;             PG8_LDA(At, 0, 1); PG8_STAGE(PG8_SB(0, 0), b2, voffB); PG8_STAGE(PG8_SB(0, 1), b2 + hstep, voffB); PG8_STAGE(PG8_SA(0, 0), a2, voffA);
;             PG8_WAIT_V(8); PG8_WAIT_L(0); PG8_BAR; PG8_MMA(1, 0, At, B0); PG8_MMA(1, 1, At, B1); PG8_BAR; PG8_SCHED;
.LBB0_812:
	s_add_i32 s16, s15, 2
	s_add_u32 s50, s8, 0x100
	s_addc_u32 s51, s9, 0
	s_add_i32 s17, 0, 0x10000
	s_cmp_eq_u32 s12, s15
	s_cselect_b32 s55, s4, s51
	s_cselect_b32 s54, s5, s50
	s_cselect_b32 s53, s10, s14
	s_cselect_b32 s52, s11, s13
	s_add_i32 s15, 0, 0x14000
	v_add_u32_e32 v158, s17, v164
	v_add_u32_e32 v162, s15, v164
	ds_read_b128 v[146:149], v158
	ds_read_b128 v[150:153], v158 offset:1024
	ds_read_b128 v[154:157], v158 offset:2048
	ds_read_b128 v[158:161], v158 offset:3072
	ds_read_b128 v[184:187], v162
	ds_read_b128 v[188:191], v162 offset:1024
	ds_read_b128 v[192:195], v162 offset:2048
	ds_read_b128 v[196:199], v162 offset:3072
	v_lshl_add_u64 v[162:163], s[8:9], 0, v[142:143]
	s_add_i32 m0, s26, 0xc000
	ds_read_b128 v[200:203], v166
	ds_read_b128 v[204:207], v166 offset:1024
	ds_read_b128 v[208:211], v166 offset:2048
	ds_read_b128 v[212:215], v166 offset:3072
	ds_read_b128 v[216:219], v166 offset:4096
	ds_read_b128 v[220:223], v166 offset:5120
	ds_read_b128 v[224:227], v166 offset:6144
	ds_read_b128 v[228:231], v166 offset:7168
	global_load_lds_dwordx4 v[162:163], off
	v_lshl_add_u64 v[162:163], s[8:9], 0, v[144:145]
	s_add_i32 m0, s26, 0xe000
	s_nop 0
	global_load_lds_dwordx4 v[162:163], off
	s_waitcnt vmcnt(8) lgkmcnt(0)
	s_setprio 1
	s_barrier
	v_mfma_f32_16x16x32_bf16 v[124:127], v[146:149], v[200:203], v[124:127]
	v_mfma_f32_16x16x32_bf16 v[92:95], v[154:157], v[200:203], v[92:95]
	v_mfma_f32_16x16x32_bf16 v[120:123], v[146:149], v[208:211], v[120:123]
	v_mfma_f32_16x16x32_bf16 v[88:91], v[154:157], v[208:211], v[88:91]
	v_mfma_f32_16x16x32_bf16 v[116:119], v[146:149], v[216:219], v[116:119]
	v_mfma_f32_16x16x32_bf16 v[84:87], v[154:157], v[216:219], v[84:87]
	v_mfma_f32_16x16x32_bf16 v[112:115], v[146:149], v[224:227], v[112:115]
	v_mfma_f32_16x16x32_bf16 v[80:83], v[154:157], v[224:227], v[80:83]
	v_mfma_f32_16x16x32_bf16 v[124:127], v[150:153], v[204:207], v[124:127]
	v_mfma_f32_16x16x32_bf16 v[92:95], v[158:161], v[204:207], v[92:95]
	v_mfma_f32_16x16x32_bf16 v[120:123], v[150:153], v[212:215], v[120:123]
	v_mfma_f32_16x16x32_bf16 v[88:91], v[158:161], v[212:215], v[88:91]
	v_mfma_f32_16x16x32_bf16 v[116:119], v[150:153], v[220:223], v[116:119]
	v_mfma_f32_16x16x32_bf16 v[84:87], v[158:161], v[220:223], v[84:87]
	v_mfma_f32_16x16x32_bf16 v[112:115], v[150:153], v[228:231], v[112:115]
	v_mfma_f32_16x16x32_bf16 v[80:83], v[158:161], v[228:231], v[80:83]
	s_setprio 0
	s_setprio 1
	v_mfma_f32_16x16x32_bf16 v[64:67], v[184:187], v[200:203], v[64:67]
	v_mfma_f32_16x16x32_bf16 v[40:43], v[192:195], v[200:203], v[40:43]
	v_mfma_f32_16x16x32_bf16 v[56:59], v[184:187], v[208:211], v[56:59]
	v_mfma_f32_16x16x32_bf16 v[32:35], v[192:195], v[208:211], v[32:35]
	v_mfma_f32_16x16x32_bf16 v[52:55], v[184:187], v[216:219], v[52:55]
	v_mfma_f32_16x16x32_bf16 v[24:27], v[192:195], v[216:219], v[24:27]
	v_mfma_f32_16x16x32_bf16 v[48:51], v[184:187], v[224:227], v[48:51]
	v_mfma_f32_16x16x32_bf16 v[16:19], v[192:195], v[224:227], v[16:19]
	v_mfma_f32_16x16x32_bf16 v[64:67], v[188:191], v[204:207], v[64:67]
	v_mfma_f32_16x16x32_bf16 v[40:43], v[196:199], v[204:207], v[40:43]
	v_mfma_f32_16x16x32_bf16 v[56:59], v[188:191], v[212:215], v[56:59]
	v_mfma_f32_16x16x32_bf16 v[32:35], v[196:199], v[212:215], v[32:35]
	v_mfma_f32_16x16x32_bf16 v[52:55], v[188:191], v[220:223], v[52:55]
	v_mfma_f32_16x16x32_bf16 v[24:27], v[196:199], v[220:223], v[24:27]
	v_mfma_f32_16x16x32_bf16 v[48:51], v[188:191], v[228:231], v[48:51]
	v_mfma_f32_16x16x32_bf16 v[16:19], v[196:199], v[228:231], v[16:19]
	s_barrier
	s_setprio 0
	s_add_i32 s8, s17, s3
	v_lshl_add_u64 v[162:163], s[52:53], 0, v[128:129]
	s_mov_b32 m0, s8
	ds_read_b128 v[200:203], v166 offset:16384
	ds_read_b128 v[204:207], v166 offset:17408
	ds_read_b128 v[208:211], v166 offset:18432
	ds_read_b128 v[212:215], v166 offset:19456
	ds_read_b128 v[216:219], v166 offset:20480
	ds_read_b128 v[220:223], v166 offset:21504
	ds_read_b128 v[224:227], v166 offset:22528
	ds_read_b128 v[228:231], v166 offset:23552
	global_load_lds_dwordx4 v[162:163], off
	s_add_i32 m0, s8, 0x2000
	s_add_u32 s8, s52, 0x50000
	v_lshl_add_u64 v[180:181], s[52:53], 0, v[138:139]
	s_addc_u32 s9, s53, 0
	s_add_i32 s15, s15, s3
	global_load_lds_dwordx4 v[180:181], off
	v_lshl_add_u64 v[182:183], s[8:9], 0, v[128:129]
	s_mov_b32 m0, s15
	v_lshl_add_u64 v[232:233], s[54:55], 0, v[138:139]
	global_load_lds_dwordx4 v[182:183], off
	v_lshl_add_u64 v[182:183], s[8:9], 0, v[138:139]
	s_add_i32 m0, s15, 0x2000
	s_nop 0
	global_load_lds_dwordx4 v[182:183], off
	v_lshl_add_u64 v[182:183], s[54:55], 0, v[128:129]
	s_mov_b32 m0, s26
	s_nop 0
	global_load_lds_dwordx4 v[182:183], off
	s_mov_b32 m0, s27
	s_nop 0
	global_load_lds_dwordx4 v[232:233], off
	s_waitcnt vmcnt(8) lgkmcnt(0)
	s_setprio 1
	s_barrier
; #define PG8_STAGE(bufoff, gbase, voff) do { _Pragma("unroll") for (int _i = 0; _i < 2; ++_i) \
;         __builtin_amdgcn_global_load_lds((const unsigned*)((const char*)(gbase) + (voff)[_i]), (LAS unsigned*)(lds + (bufoff) + ldsw + _i * 8192), 16, 0, 0); } while (0)
; #define PG8_LDA(dst, b, h) do { _Pragma("unroll") for (int m = 0; m < 4; ++m) _Pragma("unroll") for (int k = 0; k < 2; ++k) dst[m][k] = *(const LAS bf16x8*)(lds + PG8_SA(b, h) + aoff + m * 2048 + k * 1024); } while (0)
; #define PG8_LDB(dst, b, h) do { _Pragma("unroll") for (int n = 0; n < 2; ++n) _Pragma("unroll") for (int k = 0; k < 2; ++k) dst[n][k] = *(const LAS bf16x8*)(lds + PG8_SB(b, h) + boff + n * 2048 + k * 1024); } while (0)
; #define PG8_MMA(ai, bj, At, Bt) do { __builtin_amdgcn_s_setprio(1); _Pragma("unroll") for (int m = 0; m < 4; ++m) _Pragma("unroll") for (int n = 0; n < 2; ++n) _Pragma("unroll") for (int k = 0; k < 2; ++k) \
;         acc[ai][bj][m][n] = __builtin_amdgcn_mfma_f32_16x16x32_bf16(Bt[n][k], At[m][k], acc[ai][bj][m][n], 0, 0, 0); __builtin_amdgcn_s_setprio(0); } while (0)
; #define PG8_WAIT_V(n) asm volatile("s_waitcnt vmcnt(" #n ")" ::: "memory")
; #define PG8_WAIT_L(n) asm volatile("s_waitcnt lgkmcnt(" #n ")" ::: "memory")
; #define PG8_BAR __builtin_amdgcn_s_barrier()
; #define PG8_SCHED __builtin_amdgcn_sched_barrier(0)
; template <class Epi, class Sched>
; __device__ __forceinline__ void gemm_phase(LAS unsigned char* lds, const int K, const Sched& S, const Epi& E) {
;     ...
;             PG8_WAIT_V(8); PG8_WAIT_L(0); PG8_BAR; PG8_MMA(1, 0, At, B0); PG8_MMA(1, 1, At, B1); PG8_BAR; PG8_SCHED;
;             PG8_LDB(B0, 1, 0); PG8_LDB(B1, 1, 1); PG8_SCHED; PG8_LDA(At, 1, 0); PG8_STAGE(PG8_SA(0, 1), a2 + hstep, voffA);
;             PG8_WAIT_V(8); PG8_WAIT_L(0); PG8_BAR; PG8_MMA(0, 0, At, B0); PG8_MMA(0, 1, At, B1); PG8_BAR; PG8_SCHED;
	v_mfma_f32_16x16x32_bf16 v[108:111], v[146:149], v[200:203], v[108:111]
	v_mfma_f32_16x16x32_bf16 v[76:79], v[154:157], v[200:203], v[76:79]
	v_mfma_f32_16x16x32_bf16 v[104:107], v[146:149], v[208:211], v[104:107]
	v_mfma_f32_16x16x32_bf16 v[72:75], v[154:157], v[208:211], v[72:75]
	v_mfma_f32_16x16x32_bf16 v[100:103], v[146:149], v[216:219], v[100:103]
	v_mfma_f32_16x16x32_bf16 v[68:71], v[154:157], v[216:219], v[68:71]
	v_mfma_f32_16x16x32_bf16 v[96:99], v[146:149], v[224:227], v[96:99]
	v_mfma_f32_16x16x32_bf16 v[60:63], v[154:157], v[224:227], v[60:63]
	v_mfma_f32_16x16x32_bf16 v[108:111], v[150:153], v[204:207], v[108:111]
	v_mfma_f32_16x16x32_bf16 v[76:79], v[158:161], v[204:207], v[76:79]
	v_mfma_f32_16x16x32_bf16 v[104:107], v[150:153], v[212:215], v[104:107]
	v_mfma_f32_16x16x32_bf16 v[72:75], v[158:161], v[212:215], v[72:75]
	v_mfma_f32_16x16x32_bf16 v[100:103], v[150:153], v[220:223], v[100:103]
	v_mfma_f32_16x16x32_bf16 v[68:71], v[158:161], v[220:223], v[68:71]
	v_mfma_f32_16x16x32_bf16 v[96:99], v[150:153], v[228:231], v[96:99]
	v_mfma_f32_16x16x32_bf16 v[60:63], v[158:161], v[228:231], v[60:63]
	s_setprio 0
	s_setprio 1
	v_mfma_f32_16x16x32_bf16 v[44:47], v[184:187], v[200:203], v[44:47]
	v_mfma_f32_16x16x32_bf16 v[12:15], v[192:195], v[200:203], v[12:15]
	v_mfma_f32_16x16x32_bf16 v[36:39], v[184:187], v[208:211], v[36:39]
	v_mfma_f32_16x16x32_bf16 v[8:11], v[192:195], v[208:211], v[8:11]
	v_mfma_f32_16x16x32_bf16 v[28:31], v[184:187], v[216:219], v[28:31]
	v_mfma_f32_16x16x32_bf16 v[4:7], v[192:195], v[216:219], v[4:7]
	v_mfma_f32_16x16x32_bf16 v[20:23], v[184:187], v[224:227], v[20:23]
	v_mfma_f32_16x16x32_bf16 v[0:3], v[192:195], v[224:227], v[0:3]
	v_mfma_f32_16x16x32_bf16 v[44:47], v[188:191], v[204:207], v[44:47]
	v_mfma_f32_16x16x32_bf16 v[12:15], v[196:199], v[204:207], v[12:15]
	v_mfma_f32_16x16x32_bf16 v[36:39], v[188:191], v[212:215], v[36:39]
	v_mfma_f32_16x16x32_bf16 v[8:11], v[196:199], v[212:215], v[8:11]
	v_mfma_f32_16x16x32_bf16 v[28:31], v[188:191], v[220:223], v[28:31]
	v_mfma_f32_16x16x32_bf16 v[4:7], v[196:199], v[220:223], v[4:7]
	v_mfma_f32_16x16x32_bf16 v[20:23], v[188:191], v[228:231], v[20:23]
	v_mfma_f32_16x16x32_bf16 v[0:3], v[196:199], v[228:231], v[0:3]
	s_barrier
	s_setprio 0
	s_add_i32 s15, 0, 0x18000
	s_add_i32 s17, 0, 0x1c000
	v_add_u32_e32 v158, s15, v164
	v_add_u32_e32 v167, s17, v164
	ds_read_b128 v[146:149], v158
	ds_read_b128 v[150:153], v158 offset:1024
	ds_read_b128 v[154:157], v158 offset:2048
	ds_read_b128 v[158:161], v158 offset:3072
	ds_read_b128 v[184:187], v167
	ds_read_b128 v[188:191], v167 offset:1024
	ds_read_b128 v[192:195], v167 offset:2048
	ds_read_b128 v[196:199], v167 offset:3072
	s_add_u32 s8, s54, 0x50000
	s_addc_u32 s9, s55, 0
	s_mov_b32 m0, s56
	v_lshl_add_u64 v[234:235], s[8:9], 0, v[128:129]
	ds_read_b128 v[200:203], v166 offset:32768
	ds_read_b128 v[204:207], v166 offset:33792
	ds_read_b128 v[208:211], v166 offset:34816
	ds_read_b128 v[212:215], v166 offset:35840
	ds_read_b128 v[216:219], v166 offset:36864
	ds_read_b128 v[220:223], v166 offset:37888
	ds_read_b128 v[224:227], v166 offset:38912
	ds_read_b128 v[228:231], v166 offset:39936
	global_load_lds_dwordx4 v[234:235], off
	v_lshl_add_u64 v[234:235], s[8:9], 0, v[138:139]
	s_mov_b32 m0, s57
	s_nop 0
	global_load_lds_dwordx4 v[234:235], off
	s_waitcnt vmcnt(8) lgkmcnt(0)
	s_setprio 1
	s_barrier
	v_mfma_f32_16x16x32_bf16 v[124:127], v[146:149], v[200:203], v[124:127]
	v_mfma_f32_16x16x32_bf16 v[92:95], v[154:157], v[200:203], v[92:95]
	v_mfma_f32_16x16x32_bf16 v[120:123], v[146:149], v[208:211], v[120:123]
	v_mfma_f32_16x16x32_bf16 v[88:91], v[154:157], v[208:211], v[88:91]
	v_mfma_f32_16x16x32_bf16 v[116:119], v[146:149], v[216:219], v[116:119]
	v_mfma_f32_16x16x32_bf16 v[84:87], v[154:157], v[216:219], v[84:87]
	v_mfma_f32_16x16x32_bf16 v[112:115], v[146:149], v[224:227], v[112:115]
	v_mfma_f32_16x16x32_bf16 v[80:83], v[154:157], v[224:227], v[80:83]
	v_mfma_f32_16x16x32_bf16 v[124:127], v[150:153], v[204:207], v[124:127]
	v_mfma_f32_16x16x32_bf16 v[92:95], v[158:161], v[204:207], v[92:95]
	v_mfma_f32_16x16x32_bf16 v[120:123], v[150:153], v[212:215], v[120:123]
	v_mfma_f32_16x16x32_bf16 v[88:91], v[158:161], v[212:215], v[88:91]
	v_mfma_f32_16x16x32_bf16 v[116:119], v[150:153], v[220:223], v[116:119]
	v_mfma_f32_16x16x32_bf16 v[84:87], v[158:161], v[220:223], v[84:87]
	v_mfma_f32_16x16x32_bf16 v[112:115], v[150:153], v[228:231], v[112:115]
	v_mfma_f32_16x16x32_bf16 v[80:83], v[158:161], v[228:231], v[80:83]
	s_setprio 0
	s_setprio 1
	v_mfma_f32_16x16x32_bf16 v[64:67], v[184:187], v[200:203], v[64:67]
	v_mfma_f32_16x16x32_bf16 v[40:43], v[192:195], v[200:203], v[40:43]
	v_mfma_f32_16x16x32_bf16 v[56:59], v[184:187], v[208:211], v[56:59]
	v_mfma_f32_16x16x32_bf16 v[32:35], v[192:195], v[208:211], v[32:35]
	v_mfma_f32_16x16x32_bf16 v[52:55], v[184:187], v[216:219], v[52:55]
	v_mfma_f32_16x16x32_bf16 v[24:27], v[192:195], v[216:219], v[24:27]
	v_mfma_f32_16x16x32_bf16 v[48:51], v[184:187], v[224:227], v[48:51]
	v_mfma_f32_16x16x32_bf16 v[16:19], v[192:195], v[224:227], v[16:19]
	v_mfma_f32_16x16x32_bf16 v[64:67], v[188:191], v[204:207], v[64:67]
	v_mfma_f32_16x16x32_bf16 v[40:43], v[196:199], v[204:207], v[40:43]
	v_mfma_f32_16x16x32_bf16 v[56:59], v[188:191], v[212:215], v[56:59]
	v_mfma_f32_16x16x32_bf16 v[32:35], v[196:199], v[212:215], v[32:35]
	v_mfma_f32_16x16x32_bf16 v[52:55], v[188:191], v[220:223], v[52:55]
	v_mfma_f32_16x16x32_bf16 v[24:27], v[196:199], v[220:223], v[24:27]
	v_mfma_f32_16x16x32_bf16 v[48:51], v[188:191], v[228:231], v[48:51]
	v_mfma_f32_16x16x32_bf16 v[16:19], v[196:199], v[228:231], v[16:19]
	s_barrier
; #define PG8_STAGE(bufoff, gbase, voff) do { _Pragma("unroll") for (int _i = 0; _i < 2; ++_i) \
;         __builtin_amdgcn_global_load_lds((const unsigned*)((const char*)(gbase) + (voff)[_i]), (LAS unsigned*)(lds + (bufoff) + ldsw + _i * 8192), 16, 0, 0); } while (0)
; #define PG8_LDA(dst, b, h) do { _Pragma("unroll") for (int m = 0; m < 4; ++m) _Pragma("unroll") for (int k = 0; k < 2; ++k) dst[m][k] = *(const LAS bf16x8*)(lds + PG8_SA(b, h) + aoff + m * 2048 + k * 1024); } while (0)
; #define PG8_MMA(ai, bj, At, Bt) do { __builtin_amdgcn_s_setprio(1); _Pragma("unroll") for (int m = 0; m < 4; ++m) _Pragma("unroll") for (int n = 0; n < 2; ++n) _Pragma("unroll") for (int k = 0; k < 2; ++k) \
;         acc[ai][bj][m][n] = __builtin_amdgcn_mfma_f32_16x16x32_bf16(Bt[n][k], At[m][k], acc[ai][bj][m][n], 0, 0, 0); __builtin_amdgcn_s_setprio(0); } while (0)
; #define PG8_WAIT_V(n) asm volatile("s_waitcnt vmcnt(" #n ")" ::: "memory")
; #define PG8_WAIT_L(n) asm volatile("s_waitcnt lgkmcnt(" #n ")" ::: "memory")
; #define PG8_BAR __builtin_amdgcn_s_barrier()
; #define PG8_SCHED __builtin_amdgcn_sched_barrier(0)
; template <class Epi, class Sched>
; __device__ __forceinline__ void gemm_phase(LAS unsigned char* lds, const int K, const Sched& S, const Epi& E) {
;     ...
;             PG8_LDA(At, 1, 1); PG8_STAGE(PG8_SB(1, 0), b3, voffB); PG8_STAGE(PG8_SB(1, 1), b3 + hstep, voffB); PG8_STAGE(PG8_SA(1, 0), a3, voffA);
;             PG8_WAIT_V(8); PG8_WAIT_L(0); PG8_BAR; PG8_MMA(1, 0, At, B0); PG8_MMA(1, 1, At, B1); PG8_BAR; PG8_SCHED;
;         }
;         if (wr == 0) PG8_BAR;
	s_setprio 0
	s_add_i32 s8, s15, s3
	v_lshl_add_u64 v[162:163], v[162:163], 0, s[36:37]
	s_mov_b32 m0, s8
	ds_read_b128 v[200:203], v166 offset:49152
	ds_read_b128 v[204:207], v166 offset:50176
	ds_read_b128 v[208:211], v166 offset:51200
	ds_read_b128 v[212:215], v166 offset:52224
	ds_read_b128 v[216:219], v166 offset:53248
	ds_read_b128 v[220:223], v166 offset:54272
	ds_read_b128 v[224:227], v166 offset:55296
	ds_read_b128 v[228:231], v166 offset:56320
	global_load_lds_dwordx4 v[162:163], off
	s_add_i32 m0, s8, 0x2000
	s_add_u32 s8, s52, 0x50080
	v_lshl_add_u64 v[162:163], v[180:181], 0, s[36:37]
	s_addc_u32 s9, s53, 0
	s_add_i32 s15, s17, s3
	global_load_lds_dwordx4 v[162:163], off
	v_lshl_add_u64 v[162:163], s[8:9], 0, v[128:129]
	s_mov_b32 m0, s15
	s_nop 0
	global_load_lds_dwordx4 v[162:163], off
	v_lshl_add_u64 v[162:163], s[8:9], 0, v[138:139]
	s_add_i32 m0, s15, 0x2000
	s_nop 0
	global_load_lds_dwordx4 v[162:163], off
	v_lshl_add_u64 v[162:163], v[182:183], 0, s[36:37]
	s_mov_b32 m0, s58
	s_nop 0
	global_load_lds_dwordx4 v[162:163], off
	v_lshl_add_u64 v[162:163], v[232:233], 0, s[36:37]
	s_mov_b32 m0, s59
	s_nop 0
	global_load_lds_dwordx4 v[162:163], off
	s_waitcnt vmcnt(8) lgkmcnt(0)
	s_setprio 1
	s_barrier
	v_mfma_f32_16x16x32_bf16 v[108:111], v[146:149], v[200:203], v[108:111]
	v_mfma_f32_16x16x32_bf16 v[76:79], v[154:157], v[200:203], v[76:79]
	v_mfma_f32_16x16x32_bf16 v[104:107], v[146:149], v[208:211], v[104:107]
	v_mfma_f32_16x16x32_bf16 v[72:75], v[154:157], v[208:211], v[72:75]
	v_mfma_f32_16x16x32_bf16 v[100:103], v[146:149], v[216:219], v[100:103]
	v_mfma_f32_16x16x32_bf16 v[68:71], v[154:157], v[216:219], v[68:71]
	v_mfma_f32_16x16x32_bf16 v[96:99], v[146:149], v[224:227], v[96:99]
	v_mfma_f32_16x16x32_bf16 v[60:63], v[154:157], v[224:227], v[60:63]
	v_mfma_f32_16x16x32_bf16 v[108:111], v[150:153], v[204:207], v[108:111]
	v_mfma_f32_16x16x32_bf16 v[76:79], v[158:161], v[204:207], v[76:79]
	v_mfma_f32_16x16x32_bf16 v[104:107], v[150:153], v[212:215], v[104:107]
	v_mfma_f32_16x16x32_bf16 v[72:75], v[158:161], v[212:215], v[72:75]
	v_mfma_f32_16x16x32_bf16 v[100:103], v[150:153], v[220:223], v[100:103]
	v_mfma_f32_16x16x32_bf16 v[68:71], v[158:161], v[220:223], v[68:71]
	v_mfma_f32_16x16x32_bf16 v[96:99], v[150:153], v[228:231], v[96:99]
	v_mfma_f32_16x16x32_bf16 v[60:63], v[158:161], v[228:231], v[60:63]
	s_setprio 0
	s_setprio 1
	v_mfma_f32_16x16x32_bf16 v[44:47], v[184:187], v[200:203], v[44:47]
	v_mfma_f32_16x16x32_bf16 v[12:15], v[192:195], v[200:203], v[12:15]
	v_mfma_f32_16x16x32_bf16 v[36:39], v[184:187], v[208:211], v[36:39]
	v_mfma_f32_16x16x32_bf16 v[8:11], v[192:195], v[208:211], v[8:11]
	v_mfma_f32_16x16x32_bf16 v[28:31], v[184:187], v[216:219], v[28:31]
	v_mfma_f32_16x16x32_bf16 v[4:7], v[192:195], v[216:219], v[4:7]
	v_mfma_f32_16x16x32_bf16 v[20:23], v[184:187], v[224:227], v[20:23]
	v_mfma_f32_16x16x32_bf16 v[0:3], v[192:195], v[224:227], v[0:3]
	v_mfma_f32_16x16x32_bf16 v[44:47], v[188:191], v[204:207], v[44:47]
	v_mfma_f32_16x16x32_bf16 v[12:15], v[196:199], v[204:207], v[12:15]
	v_mfma_f32_16x16x32_bf16 v[36:39], v[188:191], v[212:215], v[36:39]
	v_mfma_f32_16x16x32_bf16 v[8:11], v[196:199], v[212:215], v[8:11]
	v_mfma_f32_16x16x32_bf16 v[28:31], v[188:191], v[220:223], v[28:31]
	v_mfma_f32_16x16x32_bf16 v[4:7], v[196:199], v[220:223], v[4:7]
	v_mfma_f32_16x16x32_bf16 v[20:23], v[188:191], v[228:231], v[20:23]
	v_mfma_f32_16x16x32_bf16 v[0:3], v[196:199], v[228:231], v[0:3]
	s_barrier
	s_setprio 0
	s_add_u32 s13, s13, 0x100
	s_addc_u32 s14, s14, 0
	s_cmp_ge_i32 s16, s2
	s_mov_b64 s[8:9], s[50:51]
	s_mov_b32 s15, s16
	s_cbranch_scc0 .LBB0_812
	s_and_b64 vcc, exec, s[40:41]
	s_cbranch_vccz .LBB0_815
	s_barrier

; #define PG8_STAGE(bufoff, gbase, voff) do { _Pragma("unroll") for (int _i = 0; _i < 2; ++_i) \
;         __builtin_amdgcn_global_load_lds((const unsigned*)((const char*)(gbase) + (voff)[_i]), (LAS unsigned*)(lds + (bufoff) + ldsw + _i * 8192), 16, 0, 0); } while (0)
; #define PG8_LDA(dst, b, h) do { _Pragma("unroll") for (int m = 0; m < 4; ++m) _Pragma("unroll") for (int k = 0; k < 2; ++k) dst[m][k] = *(const LAS bf16x8*)(lds + PG8_SA(b, h) + aoff + m * 2048 + k * 1024); } while (0)
; #define PG8_LDB(dst, b, h) do { _Pragma("unroll") for (int n = 0; n < 2; ++n) _Pragma("unroll") for (int k = 0; k < 2; ++k) dst[n][k] = *(const LAS bf16x8*)(lds + PG8_SB(b, h) + boff + n * 2048 + k * 1024); } while (0)
; #define PG8_MMA(ai, bj, At, Bt) do { __builtin_amdgcn_s_setprio(1); _Pragma("unroll") for (int m = 0; m < 4; ++m) _Pragma("unroll") for (int n = 0; n < 2; ++n) _Pragma("unroll") for (int k = 0; k < 2; ++k) \
;         acc[ai][bj][m][n] = __builtin_amdgcn_mfma_f32_16x16x32_bf16(Bt[n][k], At[m][k], acc[ai][bj][m][n], 0, 0, 0); __builtin_amdgcn_s_setprio(0); } while (0)
; #define PG8_WAIT_V(n) asm volatile("s_waitcnt vmcnt(" #n ")" ::: "memory")
; #define PG8_WAIT_L(n) asm volatile("s_waitcnt lgkmcnt(" #n ")" ::: "memory")
; #define PG8_BAR __builtin_amdgcn_s_barrier()
; #define PG8_SCHED __builtin_amdgcn_sched_barrier(0)
; template <class Epi, class Sched>
; __device__ __forceinline__ void gemm_phase(LAS unsigned char* lds, const int K, const Sched& S, const Epi& E) {
;     ...
;         for (int t = 0; t < nt; t += 2) {
;             const bool last = (t == nt - 2);
;             const char* a1 = cA + (size_t)(t + 1) * kstep;
;             const char* a2 = last ? nA : cA + (size_t)(t + 2) * kstep; const char* b2 = last ? nB : cB + (size_t)(t + 2) * kstep;
;             const char* a3 = a2 + kstep; const char* b3 = b2 + kstep;
;             PG8_LDB(B0, 0, 0); PG8_LDB(B1, 0, 1); PG8_SCHED; PG8_LDA(At, 0, 0); PG8_STAGE(PG8_SA(1, 1), a1 + hstep, voffA);
;             PG8_WAIT_V(8); PG8_WAIT_L(0); PG8_BAR; PG8_MMA(0, 0, At, B0); PG8_MMA(0, 1, At, B1); PG8_BAR; PG8_SCHED;
;             PG8_LDA(At, 0, 1); PG8_STAGE(PG8_SB(0, 0), b2, voffB); PG8_STAGE(PG8_SB(0, 1), b2 + hstep, voffB); PG8_STAGE(PG8_SA(0, 0), a2, voffA);
;             PG8_WAIT_V(8); PG8_WAIT_L(0); PG8_BAR; PG8_MMA(1, 0, At, B0); PG8_MMA(1, 1, At, B1); PG8_BAR; PG8_SCHED;
.LBB0_963:
	s_add_u32 s5, s56, 0xfffc0080
	s_addc_u32 s9, s57, -1
	s_add_i32 s10, 0, 0x10000
	s_cmp_eq_u32 s4, 12
	s_cselect_b32 s61, s53, s9
	s_cselect_b32 s60, s52, s5
	v_add_u32_e32 v150, s10, v153
	s_cselect_b32 s59, s55, s2
	s_cselect_b32 s58, s54, s1
	s_add_i32 s5, 0, 0x14000
	ds_read_b128 v[156:159], v150
	ds_read_b128 v[160:163], v150 offset:1024
	ds_read_b128 v[164:167], v150 offset:2048
	ds_read_b128 v[180:183], v150 offset:3072
	v_add_u32_e32 v150, s5, v153
	ds_read_b128 v[184:187], v150
	ds_read_b128 v[188:191], v150 offset:1024
	ds_read_b128 v[192:195], v150 offset:2048
	ds_read_b128 v[196:199], v150 offset:3072
	v_lshl_add_u64 v[150:151], s[56:57], 0, v[146:147]
	s_add_i32 m0, s66, 0xc000
	ds_read_b128 v[200:203], v154
	ds_read_b128 v[204:207], v154 offset:1024
	ds_read_b128 v[208:211], v154 offset:2048
	ds_read_b128 v[212:215], v154 offset:3072
	ds_read_b128 v[216:219], v154 offset:4096
	ds_read_b128 v[220:223], v154 offset:5120
	ds_read_b128 v[224:227], v154 offset:6144
	ds_read_b128 v[228:231], v154 offset:7168
	global_load_lds_dwordx4 v[150:151], off
	v_lshl_add_u64 v[150:151], s[56:57], 0, v[148:149]
	s_add_i32 m0, s66, 0xe000
	s_nop 0
	global_load_lds_dwordx4 v[150:151], off
	s_waitcnt vmcnt(8) lgkmcnt(0)
	s_setprio 1
	s_barrier
	v_mfma_f32_16x16x32_bf16 v[124:127], v[156:159], v[200:203], v[124:127]
	v_mfma_f32_16x16x32_bf16 v[116:119], v[164:167], v[200:203], v[116:119]
	v_mfma_f32_16x16x32_bf16 v[108:111], v[156:159], v[208:211], v[108:111]
	v_mfma_f32_16x16x32_bf16 v[100:103], v[164:167], v[208:211], v[100:103]
	v_mfma_f32_16x16x32_bf16 v[92:95], v[156:159], v[216:219], v[92:95]
	v_mfma_f32_16x16x32_bf16 v[84:87], v[164:167], v[216:219], v[84:87]
	v_mfma_f32_16x16x32_bf16 v[76:79], v[156:159], v[224:227], v[76:79]
	v_mfma_f32_16x16x32_bf16 v[68:71], v[164:167], v[224:227], v[68:71]
	v_mfma_f32_16x16x32_bf16 v[124:127], v[160:163], v[204:207], v[124:127]
	v_mfma_f32_16x16x32_bf16 v[116:119], v[180:183], v[204:207], v[116:119]
	v_mfma_f32_16x16x32_bf16 v[108:111], v[160:163], v[212:215], v[108:111]
	v_mfma_f32_16x16x32_bf16 v[100:103], v[180:183], v[212:215], v[100:103]
	v_mfma_f32_16x16x32_bf16 v[92:95], v[160:163], v[220:223], v[92:95]
	v_mfma_f32_16x16x32_bf16 v[84:87], v[180:183], v[220:223], v[84:87]
	v_mfma_f32_16x16x32_bf16 v[76:79], v[160:163], v[228:231], v[76:79]
	v_mfma_f32_16x16x32_bf16 v[68:71], v[180:183], v[228:231], v[68:71]
	s_setprio 0
	s_setprio 1
	v_mfma_f32_16x16x32_bf16 v[120:123], v[184:187], v[200:203], v[120:123]
	v_mfma_f32_16x16x32_bf16 v[112:115], v[192:195], v[200:203], v[112:115]
	v_mfma_f32_16x16x32_bf16 v[104:107], v[184:187], v[208:211], v[104:107]
	v_mfma_f32_16x16x32_bf16 v[96:99], v[192:195], v[208:211], v[96:99]
	v_mfma_f32_16x16x32_bf16 v[88:91], v[184:187], v[216:219], v[88:91]
	v_mfma_f32_16x16x32_bf16 v[80:83], v[192:195], v[216:219], v[80:83]
	v_mfma_f32_16x16x32_bf16 v[72:75], v[184:187], v[224:227], v[72:75]
	v_mfma_f32_16x16x32_bf16 v[64:67], v[192:195], v[224:227], v[64:67]
	v_mfma_f32_16x16x32_bf16 v[120:123], v[188:191], v[204:207], v[120:123]
	v_mfma_f32_16x16x32_bf16 v[112:115], v[196:199], v[204:207], v[112:115]
	v_mfma_f32_16x16x32_bf16 v[104:107], v[188:191], v[212:215], v[104:107]
	v_mfma_f32_16x16x32_bf16 v[96:99], v[196:199], v[212:215], v[96:99]
	v_mfma_f32_16x16x32_bf16 v[88:91], v[188:191], v[220:223], v[88:91]
	v_mfma_f32_16x16x32_bf16 v[80:83], v[196:199], v[220:223], v[80:83]
	v_mfma_f32_16x16x32_bf16 v[72:75], v[188:191], v[228:231], v[72:75]
	v_mfma_f32_16x16x32_bf16 v[64:67], v[196:199], v[228:231], v[64:67]
	s_barrier
	s_setprio 0
	s_add_i32 s9, s10, s63
	v_lshl_add_u64 v[150:151], s[58:59], 0, v[142:143]
	s_mov_b32 m0, s9
	ds_read_b128 v[200:203], v154 offset:16384
	ds_read_b128 v[204:207], v154 offset:17408
	ds_read_b128 v[208:211], v154 offset:18432
	ds_read_b128 v[212:215], v154 offset:19456
	ds_read_b128 v[216:219], v154 offset:20480
	ds_read_b128 v[220:223], v154 offset:21504
	ds_read_b128 v[224:227], v154 offset:22528
	ds_read_b128 v[228:231], v154 offset:23552
	global_load_lds_dwordx4 v[150:151], off
	s_add_i32 m0, s9, 0x2000
	s_add_u32 s10, s58, 0x40000
	v_lshl_add_u64 v[232:233], s[58:59], 0, v[138:139]
	s_addc_u32 s11, s59, 0
	s_add_i32 s5, s5, s63
	global_load_lds_dwordx4 v[232:233], off
	v_lshl_add_u64 v[234:235], s[10:11], 0, v[142:143]
	s_mov_b32 m0, s5
	v_lshl_add_u64 v[236:237], s[60:61], 0, v[140:141]
	global_load_lds_dwordx4 v[234:235], off
	v_lshl_add_u64 v[234:235], s[10:11], 0, v[138:139]
	s_add_i32 m0, s5, 0x2000
	s_nop 0
	global_load_lds_dwordx4 v[234:235], off
	v_lshl_add_u64 v[234:235], s[60:61], 0, v[144:145]
	s_mov_b32 m0, s66
	s_nop 0
	global_load_lds_dwordx4 v[234:235], off
	s_mov_b32 m0, s67
	s_nop 0
	global_load_lds_dwordx4 v[236:237], off
	s_waitcnt vmcnt(8) lgkmcnt(0)
	s_setprio 1
	s_barrier
; #define PG8_STAGE(bufoff, gbase, voff) do { _Pragma("unroll") for (int _i = 0; _i < 2; ++_i) \
;         __builtin_amdgcn_global_load_lds((const unsigned*)((const char*)(gbase) + (voff)[_i]), (LAS unsigned*)(lds + (bufoff) + ldsw + _i * 8192), 16, 0, 0); } while (0)
; #define PG8_LDA(dst, b, h) do { _Pragma("unroll") for (int m = 0; m < 4; ++m) _Pragma("unroll") for (int k = 0; k < 2; ++k) dst[m][k] = *(const LAS bf16x8*)(lds + PG8_SA(b, h) + aoff + m * 2048 + k * 1024); } while (0)
; #define PG8_LDB(dst, b, h) do { _Pragma("unroll") for (int n = 0; n < 2; ++n) _Pragma("unroll") for (int k = 0; k < 2; ++k) dst[n][k] = *(const LAS bf16x8*)(lds + PG8_SB(b, h) + boff + n * 2048 + k * 1024); } while (0)
; #define PG8_MMA(ai, bj, At, Bt) do { __builtin_amdgcn_s_setprio(1); _Pragma("unroll") for (int m = 0; m < 4; ++m) _Pragma("unroll") for (int n = 0; n < 2; ++n) _Pragma("unroll") for (int k = 0; k < 2; ++k) \
;         acc[ai][bj][m][n] = __builtin_amdgcn_mfma_f32_16x16x32_bf16(Bt[n][k], At[m][k], acc[ai][bj][m][n], 0, 0, 0); __builtin_amdgcn_s_setprio(0); } while (0)
; #define PG8_WAIT_V(n) asm volatile("s_waitcnt vmcnt(" #n ")" ::: "memory")
; #define PG8_WAIT_L(n) asm volatile("s_waitcnt lgkmcnt(" #n ")" ::: "memory")
; #define PG8_BAR __builtin_amdgcn_s_barrier()
; #define PG8_SCHED __builtin_amdgcn_sched_barrier(0)
; template <class Epi, class Sched>
; __device__ __forceinline__ void gemm_phase(LAS unsigned char* lds, const int K, const Sched& S, const Epi& E) {
;     ...
;             PG8_WAIT_V(8); PG8_WAIT_L(0); PG8_BAR; PG8_MMA(1, 0, At, B0); PG8_MMA(1, 1, At, B1); PG8_BAR; PG8_SCHED;
;             PG8_LDB(B0, 1, 0); PG8_LDB(B1, 1, 1); PG8_SCHED; PG8_LDA(At, 1, 0); PG8_STAGE(PG8_SA(0, 1), a2 + hstep, voffA);
;             PG8_WAIT_V(8); PG8_WAIT_L(0); PG8_BAR; PG8_MMA(0, 0, At, B0); PG8_MMA(0, 1, At, B1); PG8_BAR; PG8_SCHED;
	v_mfma_f32_16x16x32_bf16 v[60:63], v[156:159], v[200:203], v[60:63]
	v_mfma_f32_16x16x32_bf16 v[52:55], v[164:167], v[200:203], v[52:55]
	v_mfma_f32_16x16x32_bf16 v[44:47], v[156:159], v[208:211], v[44:47]
	v_mfma_f32_16x16x32_bf16 v[36:39], v[164:167], v[208:211], v[36:39]
	v_mfma_f32_16x16x32_bf16 v[28:31], v[156:159], v[216:219], v[28:31]
	v_mfma_f32_16x16x32_bf16 v[20:23], v[164:167], v[216:219], v[20:23]
	v_mfma_f32_16x16x32_bf16 v[12:15], v[156:159], v[224:227], v[12:15]
	v_mfma_f32_16x16x32_bf16 v[4:7], v[164:167], v[224:227], v[4:7]
	v_mfma_f32_16x16x32_bf16 v[60:63], v[160:163], v[204:207], v[60:63]
	v_mfma_f32_16x16x32_bf16 v[52:55], v[180:183], v[204:207], v[52:55]
	v_mfma_f32_16x16x32_bf16 v[44:47], v[160:163], v[212:215], v[44:47]
	v_mfma_f32_16x16x32_bf16 v[36:39], v[180:183], v[212:215], v[36:39]
	v_mfma_f32_16x16x32_bf16 v[28:31], v[160:163], v[220:223], v[28:31]
	v_mfma_f32_16x16x32_bf16 v[20:23], v[180:183], v[220:223], v[20:23]
	v_mfma_f32_16x16x32_bf16 v[12:15], v[160:163], v[228:231], v[12:15]
	v_mfma_f32_16x16x32_bf16 v[4:7], v[180:183], v[228:231], v[4:7]
	s_setprio 0
	s_setprio 1
	v_mfma_f32_16x16x32_bf16 v[56:59], v[184:187], v[200:203], v[56:59]
	v_mfma_f32_16x16x32_bf16 v[48:51], v[192:195], v[200:203], v[48:51]
	v_mfma_f32_16x16x32_bf16 v[40:43], v[184:187], v[208:211], v[40:43]
	v_mfma_f32_16x16x32_bf16 v[32:35], v[192:195], v[208:211], v[32:35]
	v_mfma_f32_16x16x32_bf16 v[24:27], v[184:187], v[216:219], v[24:27]
	v_mfma_f32_16x16x32_bf16 v[16:19], v[192:195], v[216:219], v[16:19]
	v_mfma_f32_16x16x32_bf16 v[8:11], v[184:187], v[224:227], v[8:11]
	v_mfma_f32_16x16x32_bf16 v[0:3], v[192:195], v[224:227], v[0:3]
	v_mfma_f32_16x16x32_bf16 v[56:59], v[188:191], v[204:207], v[56:59]
	v_mfma_f32_16x16x32_bf16 v[48:51], v[196:199], v[204:207], v[48:51]
	v_mfma_f32_16x16x32_bf16 v[40:43], v[188:191], v[212:215], v[40:43]
	v_mfma_f32_16x16x32_bf16 v[32:35], v[196:199], v[212:215], v[32:35]
	v_mfma_f32_16x16x32_bf16 v[24:27], v[188:191], v[220:223], v[24:27]
	v_mfma_f32_16x16x32_bf16 v[16:19], v[196:199], v[220:223], v[16:19]
	v_mfma_f32_16x16x32_bf16 v[8:11], v[188:191], v[228:231], v[8:11]
	v_mfma_f32_16x16x32_bf16 v[0:3], v[196:199], v[228:231], v[0:3]
	s_barrier
	s_setprio 0
	s_add_i32 s5, 0, 0x18000
	v_add_u32_e32 v155, s5, v153
	s_add_i32 s9, 0, 0x1c000
	ds_read_b128 v[156:159], v155
	ds_read_b128 v[160:163], v155 offset:1024
	ds_read_b128 v[164:167], v155 offset:2048
	ds_read_b128 v[180:183], v155 offset:3072
	v_add_u32_e32 v155, s9, v153
	ds_read_b128 v[184:187], v155
	ds_read_b128 v[188:191], v155 offset:1024
	ds_read_b128 v[192:195], v155 offset:2048
	ds_read_b128 v[196:199], v155 offset:3072
	s_add_u32 s10, s60, 0x40000
	s_addc_u32 s11, s61, 0
	s_mov_b32 m0, s68
	v_lshl_add_u64 v[238:239], s[10:11], 0, v[144:145]
	ds_read_b128 v[200:203], v154 offset:32768
	ds_read_b128 v[204:207], v154 offset:33792
	ds_read_b128 v[208:211], v154 offset:34816
	ds_read_b128 v[212:215], v154 offset:35840
	ds_read_b128 v[216:219], v154 offset:36864
	ds_read_b128 v[220:223], v154 offset:37888
	ds_read_b128 v[224:227], v154 offset:38912
	ds_read_b128 v[228:231], v154 offset:39936
	global_load_lds_dwordx4 v[238:239], off
	v_lshl_add_u64 v[238:239], s[10:11], 0, v[140:141]
	s_mov_b32 m0, s69
	s_nop 0
	global_load_lds_dwordx4 v[238:239], off
	s_waitcnt vmcnt(8) lgkmcnt(0)
	s_setprio 1
	s_barrier
	v_mfma_f32_16x16x32_bf16 v[124:127], v[156:159], v[200:203], v[124:127]
	v_mfma_f32_16x16x32_bf16 v[116:119], v[164:167], v[200:203], v[116:119]
	v_mfma_f32_16x16x32_bf16 v[108:111], v[156:159], v[208:211], v[108:111]
	v_mfma_f32_16x16x32_bf16 v[100:103], v[164:167], v[208:211], v[100:103]
	v_mfma_f32_16x16x32_bf16 v[92:95], v[156:159], v[216:219], v[92:95]
	v_mfma_f32_16x16x32_bf16 v[84:87], v[164:167], v[216:219], v[84:87]
	v_mfma_f32_16x16x32_bf16 v[76:79], v[156:159], v[224:227], v[76:79]
	v_mfma_f32_16x16x32_bf16 v[68:71], v[164:167], v[224:227], v[68:71]
	v_mfma_f32_16x16x32_bf16 v[124:127], v[160:163], v[204:207], v[124:127]
	v_mfma_f32_16x16x32_bf16 v[116:119], v[180:183], v[204:207], v[116:119]
	v_mfma_f32_16x16x32_bf16 v[108:111], v[160:163], v[212:215], v[108:111]
	v_mfma_f32_16x16x32_bf16 v[100:103], v[180:183], v[212:215], v[100:103]
	v_mfma_f32_16x16x32_bf16 v[92:95], v[160:163], v[220:223], v[92:95]
	v_mfma_f32_16x16x32_bf16 v[84:87], v[180:183], v[220:223], v[84:87]
	v_mfma_f32_16x16x32_bf16 v[76:79], v[160:163], v[228:231], v[76:79]
	v_mfma_f32_16x16x32_bf16 v[68:71], v[180:183], v[228:231], v[68:71]
	s_setprio 0
	s_setprio 1
	v_mfma_f32_16x16x32_bf16 v[120:123], v[184:187], v[200:203], v[120:123]
	v_mfma_f32_16x16x32_bf16 v[112:115], v[192:195], v[200:203], v[112:115]
	v_mfma_f32_16x16x32_bf16 v[104:107], v[184:187], v[208:211], v[104:107]
	v_mfma_f32_16x16x32_bf16 v[96:99], v[192:195], v[208:211], v[96:99]
	v_mfma_f32_16x16x32_bf16 v[88:91], v[184:187], v[216:219], v[88:91]
	v_mfma_f32_16x16x32_bf16 v[80:83], v[192:195], v[216:219], v[80:83]
	v_mfma_f32_16x16x32_bf16 v[72:75], v[184:187], v[224:227], v[72:75]
	v_mfma_f32_16x16x32_bf16 v[64:67], v[192:195], v[224:227], v[64:67]
	v_mfma_f32_16x16x32_bf16 v[120:123], v[188:191], v[204:207], v[120:123]
	v_mfma_f32_16x16x32_bf16 v[112:115], v[196:199], v[204:207], v[112:115]
	v_mfma_f32_16x16x32_bf16 v[104:107], v[188:191], v[212:215], v[104:107]
	v_mfma_f32_16x16x32_bf16 v[96:99], v[196:199], v[212:215], v[96:99]
	v_mfma_f32_16x16x32_bf16 v[88:91], v[188:191], v[220:223], v[88:91]
	v_mfma_f32_16x16x32_bf16 v[80:83], v[196:199], v[220:223], v[80:83]
	v_mfma_f32_16x16x32_bf16 v[72:75], v[188:191], v[228:231], v[72:75]
	v_mfma_f32_16x16x32_bf16 v[64:67], v[196:199], v[228:231], v[64:67]
	s_barrier
; #define PG8_STAGE(bufoff, gbase, voff) do { _Pragma("unroll") for (int _i = 0; _i < 2; ++_i) \
;         __builtin_amdgcn_global_load_lds((const unsigned*)((const char*)(gbase) + (voff)[_i]), (LAS unsigned*)(lds + (bufoff) + ldsw + _i * 8192), 16, 0, 0); } while (0)
; #define PG8_LDA(dst, b, h) do { _Pragma("unroll") for (int m = 0; m < 4; ++m) _Pragma("unroll") for (int k = 0; k < 2; ++k) dst[m][k] = *(const LAS bf16x8*)(lds + PG8_SA(b, h) + aoff + m * 2048 + k * 1024); } while (0)
; #define PG8_MMA(ai, bj, At, Bt) do { __builtin_amdgcn_s_setprio(1); _Pragma("unroll") for (int m = 0; m < 4; ++m) _Pragma("unroll") for (int n = 0; n < 2; ++n) _Pragma("unroll") for (int k = 0; k < 2; ++k) \
;         acc[ai][bj][m][n] = __builtin_amdgcn_mfma_f32_16x16x32_bf16(Bt[n][k], At[m][k], acc[ai][bj][m][n], 0, 0, 0); __builtin_amdgcn_s_setprio(0); } while (0)
; #define PG8_WAIT_V(n) asm volatile("s_waitcnt vmcnt(" #n ")" ::: "memory")
; #define PG8_WAIT_L(n) asm volatile("s_waitcnt lgkmcnt(" #n ")" ::: "memory")
; #define PG8_BAR __builtin_amdgcn_s_barrier()
; #define PG8_SCHED __builtin_amdgcn_sched_barrier(0)
; template <class Epi, class Sched>
; __device__ __forceinline__ void gemm_phase(LAS unsigned char* lds, const int K, const Sched& S, const Epi& E) {
;     ...
;             PG8_LDA(At, 1, 1); PG8_STAGE(PG8_SB(1, 0), b3, voffB); PG8_STAGE(PG8_SB(1, 1), b3 + hstep, voffB); PG8_STAGE(PG8_SA(1, 0), a3, voffA);
;             PG8_WAIT_V(8); PG8_WAIT_L(0); PG8_BAR; PG8_MMA(1, 0, At, B0); PG8_MMA(1, 1, At, B1); PG8_BAR; PG8_SCHED;
;         }
;         if (wr == 0) PG8_BAR;
	s_setprio 0
	s_add_i32 s5, s5, s63
	v_lshl_add_u64 v[150:151], v[150:151], 0, s[36:37]
	s_mov_b32 m0, s5
	ds_read_b128 v[200:203], v154 offset:49152
	ds_read_b128 v[204:207], v154 offset:50176
	ds_read_b128 v[208:211], v154 offset:51200
	ds_read_b128 v[212:215], v154 offset:52224
	ds_read_b128 v[216:219], v154 offset:53248
	ds_read_b128 v[220:223], v154 offset:54272
	ds_read_b128 v[224:227], v154 offset:55296
	ds_read_b128 v[228:231], v154 offset:56320
	global_load_lds_dwordx4 v[150:151], off
	s_add_i32 m0, s5, 0x2000
	s_add_u32 s10, s58, 0x40080
	v_lshl_add_u64 v[150:151], v[232:233], 0, s[36:37]
	s_addc_u32 s11, s59, 0
	s_add_i32 s5, s9, s63
	global_load_lds_dwordx4 v[150:151], off
	v_lshl_add_u64 v[150:151], s[10:11], 0, v[142:143]
	s_mov_b32 m0, s5
	s_nop 0
	global_load_lds_dwordx4 v[150:151], off
	v_lshl_add_u64 v[150:151], s[10:11], 0, v[138:139]
	s_add_i32 m0, s5, 0x2000
	s_nop 0
	global_load_lds_dwordx4 v[150:151], off
	v_lshl_add_u64 v[150:151], v[234:235], 0, s[36:37]
	s_mov_b32 m0, s70
	s_nop 0
	global_load_lds_dwordx4 v[150:151], off
	v_lshl_add_u64 v[150:151], v[236:237], 0, s[36:37]
	s_mov_b32 m0, s71
	s_nop 0
	global_load_lds_dwordx4 v[150:151], off
	s_waitcnt vmcnt(8) lgkmcnt(0)
	s_setprio 1
	s_barrier
	v_mfma_f32_16x16x32_bf16 v[60:63], v[156:159], v[200:203], v[60:63]
	v_mfma_f32_16x16x32_bf16 v[52:55], v[164:167], v[200:203], v[52:55]
	v_mfma_f32_16x16x32_bf16 v[44:47], v[156:159], v[208:211], v[44:47]
	v_mfma_f32_16x16x32_bf16 v[36:39], v[164:167], v[208:211], v[36:39]
	v_mfma_f32_16x16x32_bf16 v[28:31], v[156:159], v[216:219], v[28:31]
	v_mfma_f32_16x16x32_bf16 v[20:23], v[164:167], v[216:219], v[20:23]
	v_mfma_f32_16x16x32_bf16 v[12:15], v[156:159], v[224:227], v[12:15]
	v_mfma_f32_16x16x32_bf16 v[4:7], v[164:167], v[224:227], v[4:7]
	v_mfma_f32_16x16x32_bf16 v[60:63], v[160:163], v[204:207], v[60:63]
	v_mfma_f32_16x16x32_bf16 v[52:55], v[180:183], v[204:207], v[52:55]
	v_mfma_f32_16x16x32_bf16 v[44:47], v[160:163], v[212:215], v[44:47]
	v_mfma_f32_16x16x32_bf16 v[36:39], v[180:183], v[212:215], v[36:39]
	v_mfma_f32_16x16x32_bf16 v[28:31], v[160:163], v[220:223], v[28:31]
	v_mfma_f32_16x16x32_bf16 v[20:23], v[180:183], v[220:223], v[20:23]
	v_mfma_f32_16x16x32_bf16 v[12:15], v[160:163], v[228:231], v[12:15]
	v_mfma_f32_16x16x32_bf16 v[4:7], v[180:183], v[228:231], v[4:7]
	s_setprio 0
	s_setprio 1
	v_mfma_f32_16x16x32_bf16 v[56:59], v[184:187], v[200:203], v[56:59]
	v_mfma_f32_16x16x32_bf16 v[48:51], v[192:195], v[200:203], v[48:51]
	v_mfma_f32_16x16x32_bf16 v[40:43], v[184:187], v[208:211], v[40:43]
	v_mfma_f32_16x16x32_bf16 v[32:35], v[192:195], v[208:211], v[32:35]
	v_mfma_f32_16x16x32_bf16 v[24:27], v[184:187], v[216:219], v[24:27]
	v_mfma_f32_16x16x32_bf16 v[16:19], v[192:195], v[216:219], v[16:19]
	v_mfma_f32_16x16x32_bf16 v[8:11], v[184:187], v[224:227], v[8:11]
	v_mfma_f32_16x16x32_bf16 v[0:3], v[192:195], v[224:227], v[0:3]
	v_mfma_f32_16x16x32_bf16 v[56:59], v[188:191], v[204:207], v[56:59]
	v_mfma_f32_16x16x32_bf16 v[48:51], v[196:199], v[204:207], v[48:51]
	v_mfma_f32_16x16x32_bf16 v[40:43], v[188:191], v[212:215], v[40:43]
	v_mfma_f32_16x16x32_bf16 v[32:35], v[196:199], v[212:215], v[32:35]
	v_mfma_f32_16x16x32_bf16 v[24:27], v[188:191], v[220:223], v[24:27]
	v_mfma_f32_16x16x32_bf16 v[16:19], v[196:199], v[220:223], v[16:19]
	v_mfma_f32_16x16x32_bf16 v[8:11], v[188:191], v[228:231], v[8:11]
	v_mfma_f32_16x16x32_bf16 v[0:3], v[196:199], v[228:231], v[0:3]
	s_barrier
	s_setprio 0
	s_add_i32 s4, s4, 2
	s_add_u32 s56, s56, 0x100
	s_addc_u32 s57, s57, 0
	s_add_u32 s1, s1, 0x100
	s_addc_u32 s2, s2, 0
	s_cmp_gt_u32 s4, 13
	s_cbranch_scc0 .LBB0_963
	s_and_b64 vcc, exec, s[46:47]
	s_cbranch_vccz .LBB0_966
	s_barrier

; #define PG8_STAGE(bufoff, gbase, voff) do { _Pragma("unroll") for (int _i = 0; _i < 2; ++_i) \
;         __builtin_amdgcn_global_load_lds((const unsigned*)((const char*)(gbase) + (voff)[_i]), (LAS unsigned*)(lds + (bufoff) + ldsw + _i * 8192), 16, 0, 0); } while (0)
; #define PG8_LDA(dst, b, h) do { _Pragma("unroll") for (int m = 0; m < 4; ++m) _Pragma("unroll") for (int k = 0; k < 2; ++k) dst[m][k] = *(const LAS bf16x8*)(lds + PG8_SA(b, h) + aoff + m * 2048 + k * 1024); } while (0)
; #define PG8_LDB(dst, b, h) do { _Pragma("unroll") for (int n = 0; n < 2; ++n) _Pragma("unroll") for (int k = 0; k < 2; ++k) dst[n][k] = *(const LAS bf16x8*)(lds + PG8_SB(b, h) + boff + n * 2048 + k * 1024); } while (0)
; #define PG8_MMA(ai, bj, At, Bt) do { __builtin_amdgcn_s_setprio(1); _Pragma("unroll") for (int m = 0; m < 4; ++m) _Pragma("unroll") for (int n = 0; n < 2; ++n) _Pragma("unroll") for (int k = 0; k < 2; ++k) \
;         acc[ai][bj][m][n] = __builtin_amdgcn_mfma_f32_16x16x32_bf16(Bt[n][k], At[m][k], acc[ai][bj][m][n], 0, 0, 0); __builtin_amdgcn_s_setprio(0); } while (0)
; #define PG8_WAIT_V(n) asm volatile("s_waitcnt vmcnt(" #n ")" ::: "memory")
; #define PG8_WAIT_L(n) asm volatile("s_waitcnt lgkmcnt(" #n ")" ::: "memory")
; #define PG8_BAR __builtin_amdgcn_s_barrier()
; #define PG8_SCHED __builtin_amdgcn_sched_barrier(0)
; template <class Epi, class Sched>
; __device__ __forceinline__ void gemm_phase(LAS unsigned char* lds, const int K, const Sched& S, const Epi& E) {
;     ...
;         for (int t = 0; t < nt; t += 2) {
;             const bool last = (t == nt - 2);
;             const char* a1 = cA + (size_t)(t + 1) * kstep;
;             const char* a2 = last ? nA : cA + (size_t)(t + 2) * kstep; const char* b2 = last ? nB : cB + (size_t)(t + 2) * kstep;
;             const char* a3 = a2 + kstep; const char* b3 = b2 + kstep;
;             PG8_LDB(B0, 0, 0); PG8_LDB(B1, 0, 1); PG8_SCHED; PG8_LDA(At, 0, 0); PG8_STAGE(PG8_SA(1, 1), a1 + hstep, voffA);
;             PG8_WAIT_V(8); PG8_WAIT_L(0); PG8_BAR; PG8_MMA(0, 0, At, B0); PG8_MMA(0, 1, At, B1); PG8_BAR; PG8_SCHED;
;             PG8_LDA(At, 0, 1); PG8_STAGE(PG8_SB(0, 0), b2, voffB); PG8_STAGE(PG8_SB(0, 1), b2 + hstep, voffB); PG8_STAGE(PG8_SA(0, 0), a2, voffA);
;             PG8_WAIT_V(8); PG8_WAIT_L(0); PG8_BAR; PG8_MMA(1, 0, At, B0); PG8_MMA(1, 1, At, B1); PG8_BAR; PG8_SCHED;
.LBB0_1073:
	s_add_i32 s13, s12, 2
	s_add_u32 s52, s8, 0x100
	s_addc_u32 s53, s9, 0
	s_add_i32 s14, 0, 0x10000
	s_cmp_eq_u32 s5, s12
	s_cselect_b32 s57, s0, s53
	s_cselect_b32 s56, s1, s52
	s_cselect_b32 s55, s2, s11
	s_cselect_b32 s54, s4, s10
	s_add_i32 s12, 0, 0x14000
	v_add_u32_e32 v158, s14, v164
	v_add_u32_e32 v162, s12, v164
	ds_read_b128 v[146:149], v158
	ds_read_b128 v[150:153], v158 offset:1024
	ds_read_b128 v[154:157], v158 offset:2048
	ds_read_b128 v[158:161], v158 offset:3072
	ds_read_b128 v[180:183], v162
	ds_read_b128 v[184:187], v162 offset:1024
	ds_read_b128 v[188:191], v162 offset:2048
	ds_read_b128 v[192:195], v162 offset:3072
	v_lshl_add_u64 v[162:163], s[8:9], 0, v[142:143]
	s_add_i32 m0, s61, 0xc000
	ds_read_b128 v[196:199], v166
	ds_read_b128 v[200:203], v166 offset:1024
	ds_read_b128 v[204:207], v166 offset:2048
	ds_read_b128 v[208:211], v166 offset:3072
	ds_read_b128 v[212:215], v166 offset:4096
	ds_read_b128 v[216:219], v166 offset:5120
	ds_read_b128 v[220:223], v166 offset:6144
	ds_read_b128 v[224:227], v166 offset:7168
	global_load_lds_dwordx4 v[162:163], off
	v_lshl_add_u64 v[162:163], s[8:9], 0, v[144:145]
	s_add_i32 m0, s61, 0xe000
	s_nop 0
	global_load_lds_dwordx4 v[162:163], off
	s_waitcnt vmcnt(8) lgkmcnt(0)
	s_setprio 1
	s_barrier
	v_mfma_f32_16x16x32_bf16 v[124:127], v[146:149], v[196:199], v[124:127]
	v_mfma_f32_16x16x32_bf16 v[92:95], v[154:157], v[196:199], v[92:95]
	v_mfma_f32_16x16x32_bf16 v[120:123], v[146:149], v[204:207], v[120:123]
	v_mfma_f32_16x16x32_bf16 v[88:91], v[154:157], v[204:207], v[88:91]
	v_mfma_f32_16x16x32_bf16 v[116:119], v[146:149], v[212:215], v[116:119]
	v_mfma_f32_16x16x32_bf16 v[84:87], v[154:157], v[212:215], v[84:87]
	v_mfma_f32_16x16x32_bf16 v[112:115], v[146:149], v[220:223], v[112:115]
	v_mfma_f32_16x16x32_bf16 v[80:83], v[154:157], v[220:223], v[80:83]
	v_mfma_f32_16x16x32_bf16 v[124:127], v[150:153], v[200:203], v[124:127]
	v_mfma_f32_16x16x32_bf16 v[92:95], v[158:161], v[200:203], v[92:95]
	v_mfma_f32_16x16x32_bf16 v[120:123], v[150:153], v[208:211], v[120:123]
	v_mfma_f32_16x16x32_bf16 v[88:91], v[158:161], v[208:211], v[88:91]
	v_mfma_f32_16x16x32_bf16 v[116:119], v[150:153], v[216:219], v[116:119]
	v_mfma_f32_16x16x32_bf16 v[84:87], v[158:161], v[216:219], v[84:87]
	v_mfma_f32_16x16x32_bf16 v[112:115], v[150:153], v[224:227], v[112:115]
	v_mfma_f32_16x16x32_bf16 v[80:83], v[158:161], v[224:227], v[80:83]
	s_setprio 0
	s_setprio 1
	v_mfma_f32_16x16x32_bf16 v[60:63], v[180:183], v[196:199], v[60:63]
	v_mfma_f32_16x16x32_bf16 v[28:31], v[188:191], v[196:199], v[28:31]
	v_mfma_f32_16x16x32_bf16 v[56:59], v[180:183], v[204:207], v[56:59]
	v_mfma_f32_16x16x32_bf16 v[24:27], v[188:191], v[204:207], v[24:27]
	v_mfma_f32_16x16x32_bf16 v[52:55], v[180:183], v[212:215], v[52:55]
	v_mfma_f32_16x16x32_bf16 v[20:23], v[188:191], v[212:215], v[20:23]
	v_mfma_f32_16x16x32_bf16 v[48:51], v[180:183], v[220:223], v[48:51]
	v_mfma_f32_16x16x32_bf16 v[16:19], v[188:191], v[220:223], v[16:19]
	v_mfma_f32_16x16x32_bf16 v[60:63], v[184:187], v[200:203], v[60:63]
	v_mfma_f32_16x16x32_bf16 v[28:31], v[192:195], v[200:203], v[28:31]
	v_mfma_f32_16x16x32_bf16 v[56:59], v[184:187], v[208:211], v[56:59]
	v_mfma_f32_16x16x32_bf16 v[24:27], v[192:195], v[208:211], v[24:27]
	v_mfma_f32_16x16x32_bf16 v[52:55], v[184:187], v[216:219], v[52:55]
	v_mfma_f32_16x16x32_bf16 v[20:23], v[192:195], v[216:219], v[20:23]
	v_mfma_f32_16x16x32_bf16 v[48:51], v[184:187], v[224:227], v[48:51]
	v_mfma_f32_16x16x32_bf16 v[16:19], v[192:195], v[224:227], v[16:19]
	s_barrier
	s_setprio 0
	s_add_i32 s8, s14, s60
	v_lshl_add_u64 v[162:163], s[54:55], 0, v[128:129]
	s_mov_b32 m0, s8
	ds_read_b128 v[196:199], v166 offset:16384
	ds_read_b128 v[200:203], v166 offset:17408
	ds_read_b128 v[204:207], v166 offset:18432
	ds_read_b128 v[208:211], v166 offset:19456
	ds_read_b128 v[212:215], v166 offset:20480
	ds_read_b128 v[216:219], v166 offset:21504
	ds_read_b128 v[220:223], v166 offset:22528
	ds_read_b128 v[224:227], v166 offset:23552
	global_load_lds_dwordx4 v[162:163], off
	s_add_i32 m0, s8, 0x2000
	s_add_u32 s8, s54, 0xb0000
	v_lshl_add_u64 v[228:229], s[54:55], 0, v[138:139]
	s_addc_u32 s9, s55, 0
	s_add_i32 s12, s12, s60
	global_load_lds_dwordx4 v[228:229], off
	v_lshl_add_u64 v[230:231], s[8:9], 0, v[128:129]
	s_mov_b32 m0, s12
	v_lshl_add_u64 v[232:233], s[56:57], 0, v[138:139]
	global_load_lds_dwordx4 v[230:231], off
	v_lshl_add_u64 v[230:231], s[8:9], 0, v[138:139]
	s_add_i32 m0, s12, 0x2000
	s_nop 0
	global_load_lds_dwordx4 v[230:231], off
	v_lshl_add_u64 v[230:231], s[56:57], 0, v[128:129]
	s_mov_b32 m0, s61
	s_nop 0
	global_load_lds_dwordx4 v[230:231], off
	s_mov_b32 m0, s63
	s_nop 0
	global_load_lds_dwordx4 v[232:233], off
	s_waitcnt vmcnt(8) lgkmcnt(0)
	s_setprio 1
	s_barrier
; #define PG8_STAGE(bufoff, gbase, voff) do { _Pragma("unroll") for (int _i = 0; _i < 2; ++_i) \
;         __builtin_amdgcn_global_load_lds((const unsigned*)((const char*)(gbase) + (voff)[_i]), (LAS unsigned*)(lds + (bufoff) + ldsw + _i * 8192), 16, 0, 0); } while (0)
; #define PG8_LDA(dst, b, h) do { _Pragma("unroll") for (int m = 0; m < 4; ++m) _Pragma("unroll") for (int k = 0; k < 2; ++k) dst[m][k] = *(const LAS bf16x8*)(lds + PG8_SA(b, h) + aoff + m * 2048 + k * 1024); } while (0)
; #define PG8_LDB(dst, b, h) do { _Pragma("unroll") for (int n = 0; n < 2; ++n) _Pragma("unroll") for (int k = 0; k < 2; ++k) dst[n][k] = *(const LAS bf16x8*)(lds + PG8_SB(b, h) + boff + n * 2048 + k * 1024); } while (0)
; #define PG8_MMA(ai, bj, At, Bt) do { __builtin_amdgcn_s_setprio(1); _Pragma("unroll") for (int m = 0; m < 4; ++m) _Pragma("unroll") for (int n = 0; n < 2; ++n) _Pragma("unroll") for (int k = 0; k < 2; ++k) \
;         acc[ai][bj][m][n] = __builtin_amdgcn_mfma_f32_16x16x32_bf16(Bt[n][k], At[m][k], acc[ai][bj][m][n], 0, 0, 0); __builtin_amdgcn_s_setprio(0); } while (0)
; #define PG8_WAIT_V(n) asm volatile("s_waitcnt vmcnt(" #n ")" ::: "memory")
; #define PG8_WAIT_L(n) asm volatile("s_waitcnt lgkmcnt(" #n ")" ::: "memory")
; #define PG8_BAR __builtin_amdgcn_s_barrier()
; #define PG8_SCHED __builtin_amdgcn_sched_barrier(0)
; template <class Epi, class Sched>
; __device__ __forceinline__ void gemm_phase(LAS unsigned char* lds, const int K, const Sched& S, const Epi& E) {
;     ...
;             PG8_WAIT_V(8); PG8_WAIT_L(0); PG8_BAR; PG8_MMA(1, 0, At, B0); PG8_MMA(1, 1, At, B1); PG8_BAR; PG8_SCHED;
;             PG8_LDB(B0, 1, 0); PG8_LDB(B1, 1, 1); PG8_SCHED; PG8_LDA(At, 1, 0); PG8_STAGE(PG8_SA(0, 1), a2 + hstep, voffA);
;             PG8_WAIT_V(8); PG8_WAIT_L(0); PG8_BAR; PG8_MMA(0, 0, At, B0); PG8_MMA(0, 1, At, B1); PG8_BAR; PG8_SCHED;
	v_mfma_f32_16x16x32_bf16 v[108:111], v[146:149], v[196:199], v[108:111]
	v_mfma_f32_16x16x32_bf16 v[76:79], v[154:157], v[196:199], v[76:79]
	v_mfma_f32_16x16x32_bf16 v[104:107], v[146:149], v[204:207], v[104:107]
	v_mfma_f32_16x16x32_bf16 v[72:75], v[154:157], v[204:207], v[72:75]
	v_mfma_f32_16x16x32_bf16 v[100:103], v[146:149], v[212:215], v[100:103]
	v_mfma_f32_16x16x32_bf16 v[68:71], v[154:157], v[212:215], v[68:71]
	v_mfma_f32_16x16x32_bf16 v[96:99], v[146:149], v[220:223], v[96:99]
	v_mfma_f32_16x16x32_bf16 v[64:67], v[154:157], v[220:223], v[64:67]
	v_mfma_f32_16x16x32_bf16 v[108:111], v[150:153], v[200:203], v[108:111]
	v_mfma_f32_16x16x32_bf16 v[76:79], v[158:161], v[200:203], v[76:79]
	v_mfma_f32_16x16x32_bf16 v[104:107], v[150:153], v[208:211], v[104:107]
	v_mfma_f32_16x16x32_bf16 v[72:75], v[158:161], v[208:211], v[72:75]
	v_mfma_f32_16x16x32_bf16 v[100:103], v[150:153], v[216:219], v[100:103]
	v_mfma_f32_16x16x32_bf16 v[68:71], v[158:161], v[216:219], v[68:71]
	v_mfma_f32_16x16x32_bf16 v[96:99], v[150:153], v[224:227], v[96:99]
	v_mfma_f32_16x16x32_bf16 v[64:67], v[158:161], v[224:227], v[64:67]
	s_setprio 0
	s_setprio 1
	v_mfma_f32_16x16x32_bf16 v[44:47], v[180:183], v[196:199], v[44:47]
	v_mfma_f32_16x16x32_bf16 v[12:15], v[188:191], v[196:199], v[12:15]
	v_mfma_f32_16x16x32_bf16 v[40:43], v[180:183], v[204:207], v[40:43]
	v_mfma_f32_16x16x32_bf16 v[8:11], v[188:191], v[204:207], v[8:11]
	v_mfma_f32_16x16x32_bf16 v[36:39], v[180:183], v[212:215], v[36:39]
	v_mfma_f32_16x16x32_bf16 v[4:7], v[188:191], v[212:215], v[4:7]
	v_mfma_f32_16x16x32_bf16 v[32:35], v[180:183], v[220:223], v[32:35]
	v_mfma_f32_16x16x32_bf16 v[0:3], v[188:191], v[220:223], v[0:3]
	v_mfma_f32_16x16x32_bf16 v[44:47], v[184:187], v[200:203], v[44:47]
	v_mfma_f32_16x16x32_bf16 v[12:15], v[192:195], v[200:203], v[12:15]
	v_mfma_f32_16x16x32_bf16 v[40:43], v[184:187], v[208:211], v[40:43]
	v_mfma_f32_16x16x32_bf16 v[8:11], v[192:195], v[208:211], v[8:11]
	v_mfma_f32_16x16x32_bf16 v[36:39], v[184:187], v[216:219], v[36:39]
	v_mfma_f32_16x16x32_bf16 v[4:7], v[192:195], v[216:219], v[4:7]
	v_mfma_f32_16x16x32_bf16 v[32:35], v[184:187], v[224:227], v[32:35]
	v_mfma_f32_16x16x32_bf16 v[0:3], v[192:195], v[224:227], v[0:3]
	s_barrier
	s_setprio 0
	s_add_i32 s12, 0, 0x18000
	s_add_i32 s14, 0, 0x1c000
	v_add_u32_e32 v158, s12, v164
	v_add_u32_e32 v167, s14, v164
	ds_read_b128 v[146:149], v158
	ds_read_b128 v[150:153], v158 offset:1024
	ds_read_b128 v[154:157], v158 offset:2048
	ds_read_b128 v[158:161], v158 offset:3072
	ds_read_b128 v[180:183], v167
	ds_read_b128 v[184:187], v167 offset:1024
	ds_read_b128 v[188:191], v167 offset:2048
	ds_read_b128 v[192:195], v167 offset:3072
	s_add_u32 s8, s56, 0xb0000
	s_addc_u32 s9, s57, 0
	s_mov_b32 m0, s64
	v_lshl_add_u64 v[234:235], s[8:9], 0, v[128:129]
	ds_read_b128 v[196:199], v166 offset:32768
	ds_read_b128 v[200:203], v166 offset:33792
	ds_read_b128 v[204:207], v166 offset:34816
	ds_read_b128 v[208:211], v166 offset:35840
	ds_read_b128 v[212:215], v166 offset:36864
	ds_read_b128 v[216:219], v166 offset:37888
	ds_read_b128 v[220:223], v166 offset:38912
	ds_read_b128 v[224:227], v166 offset:39936
	global_load_lds_dwordx4 v[234:235], off
	v_lshl_add_u64 v[234:235], s[8:9], 0, v[138:139]
	s_mov_b32 m0, s65
	s_nop 0
	global_load_lds_dwordx4 v[234:235], off
	s_waitcnt vmcnt(8) lgkmcnt(0)
	s_setprio 1
	s_barrier
	v_mfma_f32_16x16x32_bf16 v[124:127], v[146:149], v[196:199], v[124:127]
	v_mfma_f32_16x16x32_bf16 v[92:95], v[154:157], v[196:199], v[92:95]
	v_mfma_f32_16x16x32_bf16 v[120:123], v[146:149], v[204:207], v[120:123]
	v_mfma_f32_16x16x32_bf16 v[88:91], v[154:157], v[204:207], v[88:91]
	v_mfma_f32_16x16x32_bf16 v[116:119], v[146:149], v[212:215], v[116:119]
	v_mfma_f32_16x16x32_bf16 v[84:87], v[154:157], v[212:215], v[84:87]
	v_mfma_f32_16x16x32_bf16 v[112:115], v[146:149], v[220:223], v[112:115]
	v_mfma_f32_16x16x32_bf16 v[80:83], v[154:157], v[220:223], v[80:83]
	v_mfma_f32_16x16x32_bf16 v[124:127], v[150:153], v[200:203], v[124:127]
	v_mfma_f32_16x16x32_bf16 v[92:95], v[158:161], v[200:203], v[92:95]
	v_mfma_f32_16x16x32_bf16 v[120:123], v[150:153], v[208:211], v[120:123]
	v_mfma_f32_16x16x32_bf16 v[88:91], v[158:161], v[208:211], v[88:91]
	v_mfma_f32_16x16x32_bf16 v[116:119], v[150:153], v[216:219], v[116:119]
	v_mfma_f32_16x16x32_bf16 v[84:87], v[158:161], v[216:219], v[84:87]
	v_mfma_f32_16x16x32_bf16 v[112:115], v[150:153], v[224:227], v[112:115]
	v_mfma_f32_16x16x32_bf16 v[80:83], v[158:161], v[224:227], v[80:83]
	s_setprio 0
	s_setprio 1
	v_mfma_f32_16x16x32_bf16 v[60:63], v[180:183], v[196:199], v[60:63]
	v_mfma_f32_16x16x32_bf16 v[28:31], v[188:191], v[196:199], v[28:31]
	v_mfma_f32_16x16x32_bf16 v[56:59], v[180:183], v[204:207], v[56:59]
	v_mfma_f32_16x16x32_bf16 v[24:27], v[188:191], v[204:207], v[24:27]
	v_mfma_f32_16x16x32_bf16 v[52:55], v[180:183], v[212:215], v[52:55]
	v_mfma_f32_16x16x32_bf16 v[20:23], v[188:191], v[212:215], v[20:23]
	v_mfma_f32_16x16x32_bf16 v[48:51], v[180:183], v[220:223], v[48:51]
	v_mfma_f32_16x16x32_bf16 v[16:19], v[188:191], v[220:223], v[16:19]
	v_mfma_f32_16x16x32_bf16 v[60:63], v[184:187], v[200:203], v[60:63]
	v_mfma_f32_16x16x32_bf16 v[28:31], v[192:195], v[200:203], v[28:31]
	v_mfma_f32_16x16x32_bf16 v[56:59], v[184:187], v[208:211], v[56:59]
	v_mfma_f32_16x16x32_bf16 v[24:27], v[192:195], v[208:211], v[24:27]
	v_mfma_f32_16x16x32_bf16 v[52:55], v[184:187], v[216:219], v[52:55]
	v_mfma_f32_16x16x32_bf16 v[20:23], v[192:195], v[216:219], v[20:23]
	v_mfma_f32_16x16x32_bf16 v[48:51], v[184:187], v[224:227], v[48:51]
	v_mfma_f32_16x16x32_bf16 v[16:19], v[192:195], v[224:227], v[16:19]
	s_barrier
; #define PG8_STAGE(bufoff, gbase, voff) do { _Pragma("unroll") for (int _i = 0; _i < 2; ++_i) \
;         __builtin_amdgcn_global_load_lds((const unsigned*)((const char*)(gbase) + (voff)[_i]), (LAS unsigned*)(lds + (bufoff) + ldsw + _i * 8192), 16, 0, 0); } while (0)
; #define PG8_LDA(dst, b, h) do { _Pragma("unroll") for (int m = 0; m < 4; ++m) _Pragma("unroll") for (int k = 0; k < 2; ++k) dst[m][k] = *(const LAS bf16x8*)(lds + PG8_SA(b, h) + aoff + m * 2048 + k * 1024); } while (0)
; #define PG8_MMA(ai, bj, At, Bt) do { __builtin_amdgcn_s_setprio(1); _Pragma("unroll") for (int m = 0; m < 4; ++m) _Pragma("unroll") for (int n = 0; n < 2; ++n) _Pragma("unroll") for (int k = 0; k < 2; ++k) \
;         acc[ai][bj][m][n] = __builtin_amdgcn_mfma_f32_16x16x32_bf16(Bt[n][k], At[m][k], acc[ai][bj][m][n], 0, 0, 0); __builtin_amdgcn_s_setprio(0); } while (0)
; #define PG8_WAIT_V(n) asm volatile("s_waitcnt vmcnt(" #n ")" ::: "memory")
; #define PG8_WAIT_L(n) asm volatile("s_waitcnt lgkmcnt(" #n ")" ::: "memory")
; #define PG8_BAR __builtin_amdgcn_s_barrier()
; #define PG8_SCHED __builtin_amdgcn_sched_barrier(0)
; template <class Epi, class Sched>
; __device__ __forceinline__ void gemm_phase(LAS unsigned char* lds, const int K, const Sched& S, const Epi& E) {
;     ...
;             PG8_LDA(At, 1, 1); PG8_STAGE(PG8_SB(1, 0), b3, voffB); PG8_STAGE(PG8_SB(1, 1), b3 + hstep, voffB); PG8_STAGE(PG8_SA(1, 0), a3, voffA);
;             PG8_WAIT_V(8); PG8_WAIT_L(0); PG8_BAR; PG8_MMA(1, 0, At, B0); PG8_MMA(1, 1, At, B1); PG8_BAR; PG8_SCHED;
;         }
;         if (wr == 0) PG8_BAR;
	s_setprio 0
	s_add_i32 s8, s12, s60
	v_lshl_add_u64 v[162:163], v[162:163], 0, s[36:37]
	s_mov_b32 m0, s8
	ds_read_b128 v[196:199], v166 offset:49152
	ds_read_b128 v[200:203], v166 offset:50176
	ds_read_b128 v[204:207], v166 offset:51200
	ds_read_b128 v[208:211], v166 offset:52224
	ds_read_b128 v[212:215], v166 offset:53248
	ds_read_b128 v[216:219], v166 offset:54272
	ds_read_b128 v[220:223], v166 offset:55296
	ds_read_b128 v[224:227], v166 offset:56320
	global_load_lds_dwordx4 v[162:163], off
	s_add_i32 m0, s8, 0x2000
	s_add_u32 s8, s54, 0xb0080
	v_lshl_add_u64 v[162:163], v[228:229], 0, s[36:37]
	s_addc_u32 s9, s55, 0
	s_add_i32 s12, s14, s60
	global_load_lds_dwordx4 v[162:163], off
	v_lshl_add_u64 v[162:163], s[8:9], 0, v[128:129]
	s_mov_b32 m0, s12
	s_nop 0
	global_load_lds_dwordx4 v[162:163], off
	v_lshl_add_u64 v[162:163], s[8:9], 0, v[138:139]
	s_add_i32 m0, s12, 0x2000
	s_nop 0
	global_load_lds_dwordx4 v[162:163], off
	v_lshl_add_u64 v[162:163], v[230:231], 0, s[36:37]
	s_mov_b32 m0, s68
	s_nop 0
	global_load_lds_dwordx4 v[162:163], off
	v_lshl_add_u64 v[162:163], v[232:233], 0, s[36:37]
	s_mov_b32 m0, s69
	s_nop 0
	global_load_lds_dwordx4 v[162:163], off
	s_waitcnt vmcnt(8) lgkmcnt(0)
	s_setprio 1
	s_barrier
	v_mfma_f32_16x16x32_bf16 v[108:111], v[146:149], v[196:199], v[108:111]
	v_mfma_f32_16x16x32_bf16 v[76:79], v[154:157], v[196:199], v[76:79]
	v_mfma_f32_16x16x32_bf16 v[104:107], v[146:149], v[204:207], v[104:107]
	v_mfma_f32_16x16x32_bf16 v[72:75], v[154:157], v[204:207], v[72:75]
	v_mfma_f32_16x16x32_bf16 v[100:103], v[146:149], v[212:215], v[100:103]
	v_mfma_f32_16x16x32_bf16 v[68:71], v[154:157], v[212:215], v[68:71]
	v_mfma_f32_16x16x32_bf16 v[96:99], v[146:149], v[220:223], v[96:99]
	v_mfma_f32_16x16x32_bf16 v[64:67], v[154:157], v[220:223], v[64:67]
	v_mfma_f32_16x16x32_bf16 v[108:111], v[150:153], v[200:203], v[108:111]
	v_mfma_f32_16x16x32_bf16 v[76:79], v[158:161], v[200:203], v[76:79]
	v_mfma_f32_16x16x32_bf16 v[104:107], v[150:153], v[208:211], v[104:107]
	v_mfma_f32_16x16x32_bf16 v[72:75], v[158:161], v[208:211], v[72:75]
	v_mfma_f32_16x16x32_bf16 v[100:103], v[150:153], v[216:219], v[100:103]
	v_mfma_f32_16x16x32_bf16 v[68:71], v[158:161], v[216:219], v[68:71]
	v_mfma_f32_16x16x32_bf16 v[96:99], v[150:153], v[224:227], v[96:99]
	v_mfma_f32_16x16x32_bf16 v[64:67], v[158:161], v[224:227], v[64:67]
	s_setprio 0
	s_setprio 1
	v_mfma_f32_16x16x32_bf16 v[44:47], v[180:183], v[196:199], v[44:47]
	v_mfma_f32_16x16x32_bf16 v[12:15], v[188:191], v[196:199], v[12:15]
	v_mfma_f32_16x16x32_bf16 v[40:43], v[180:183], v[204:207], v[40:43]
	v_mfma_f32_16x16x32_bf16 v[8:11], v[188:191], v[204:207], v[8:11]
	v_mfma_f32_16x16x32_bf16 v[36:39], v[180:183], v[212:215], v[36:39]
	v_mfma_f32_16x16x32_bf16 v[4:7], v[188:191], v[212:215], v[4:7]
	v_mfma_f32_16x16x32_bf16 v[32:35], v[180:183], v[220:223], v[32:35]
	v_mfma_f32_16x16x32_bf16 v[0:3], v[188:191], v[220:223], v[0:3]
	v_mfma_f32_16x16x32_bf16 v[44:47], v[184:187], v[200:203], v[44:47]
	v_mfma_f32_16x16x32_bf16 v[12:15], v[192:195], v[200:203], v[12:15]
	v_mfma_f32_16x16x32_bf16 v[40:43], v[184:187], v[208:211], v[40:43]
	v_mfma_f32_16x16x32_bf16 v[8:11], v[192:195], v[208:211], v[8:11]
	v_mfma_f32_16x16x32_bf16 v[36:39], v[184:187], v[216:219], v[36:39]
	v_mfma_f32_16x16x32_bf16 v[4:7], v[192:195], v[216:219], v[4:7]
	v_mfma_f32_16x16x32_bf16 v[32:35], v[184:187], v[224:227], v[32:35]
	v_mfma_f32_16x16x32_bf16 v[0:3], v[192:195], v[224:227], v[0:3]
	s_barrier
	s_setprio 0
	s_add_u32 s10, s10, 0x100
	s_addc_u32 s11, s11, 0
	s_cmp_ge_i32 s13, s51
	s_mov_b64 s[8:9], s[52:53]
	s_mov_b32 s12, s13
	s_cbranch_scc0 .LBB0_1073
	s_and_b64 vcc, exec, s[40:41]
	s_cbranch_vccz .LBB0_1076
